# P1: own dual-tile mainloop + own epilogue with dwordx4 stores (permlane16 swap); P9 dual-tile; PEER table conversion moved to phase 10
# speedup vs baseline: 1.0449x; 1.0264x over previous
.LBB0_104:
	v_lshrrev_b32_e32 v78, 3, v168
	v_lshrrev_b32_e32 v79, 4, v168
	v_xor_b32_e32 v79, v79, v168
	v_and_b32_e32 v79, 7, v79
	v_lshlrev_b32_e32 v79, 4, v79
	v_lshl_or_b32 v64, v78, 11, v79
	v_add_u32_e32 v66, 0x10000, v64
	v_add_u32_e32 v67, 0x20000, v64
	v_add_u32_e32 v77, 0x30000, v64
	s_load_dwordx2 s[90:91], s[0:1], 0xa0
	s_load_dwordx2 s[92:93], s[0:1], 0xa8
	v_lshrrev_b32_e32 v79, 6, v168
	s_nop 1
	v_readfirstlane_b32 s97, v79
	s_nop 3
	s_lshl_b32 s96, s97, 10
	s_add_u32 s96, s96, 16
	s_add_u32 s94, s66, s67
	s_cmp_lt_i32 s94, s68
	s_cselect_b32 s95, 1, 0
	s_cmp_lg_u64 s[8:9], 0
	s_cselect_b32 s95, 0, s95
	s_cmp_ge_u32 s94, 0x180
	s_cselect_b32 s97, 1, 0
	s_mul_i32 s100, s97, 0x180
	s_sub_u32 s100, s94, s100
	s_lshr_b32 s101, s100, 3
	s_and_b32 s100, s100, 7
	s_lshl_b32 s97, s97, 3
	s_add_u32 s100, s100, s97
	s_add_u32 s100, s100, s3
	s_cmp_lg_u32 s100, s60
	s_cselect_b32 s95, 0, s95
	s_cmp_eq_u32 s95, 1
	s_cselect_b32 s101, s101, s58
	s_mov_b32 s83, s101
	s_waitcnt lgkmcnt(0)
	s_lshl_b32 s101, s101, 18
	s_add_u32 s98, s92, s101
	s_addc_u32 s99, s93, 0
	s_lshl_b32 s94, s58, 18
	s_add_u32 s92, s92, s94
	s_addc_u32 s93, s93, 0
	s_lshl_b32 s94, s60, 18
	s_add_u32 s90, s90, s94
	s_addc_u32 s91, s91, 0
	s_barrier
	s_add_u32 m0, s96, 0x0
	s_nop 0
	global_load_lds_dwordx4 v64, s[90:91]
	s_add_u32 m0, s96, 0x1000
	s_nop 0
	global_load_lds_dwordx4 v66, s[90:91]
	s_add_u32 m0, s96, 0x2000
	s_nop 0
	global_load_lds_dwordx4 v67, s[90:91]
	s_add_u32 m0, s96, 0x3000
	s_nop 0
	global_load_lds_dwordx4 v77, s[90:91]
	s_add_u32 m0, s96, 0x4000
	s_nop 0
	global_load_lds_dwordx4 v64, s[92:93]
	s_add_u32 m0, s96, 0x5000
	s_nop 0
	global_load_lds_dwordx4 v66, s[92:93]
	s_add_u32 m0, s96, 0x6000
	s_nop 0
	global_load_lds_dwordx4 v67, s[92:93]
	s_add_u32 m0, s96, 0x7000
	s_nop 0
	global_load_lds_dwordx4 v77, s[92:93]
	s_add_u32 m0, s96, 0x8000
	s_nop 0
	global_load_lds_dwordx4 v64, s[98:99]
	s_add_u32 m0, s96, 0x9000
	s_nop 0
	global_load_lds_dwordx4 v66, s[98:99]
	s_add_u32 m0, s96, 0xa000
	s_nop 0
	global_load_lds_dwordx4 v67, s[98:99]
	s_add_u32 m0, s96, 0xb000
	s_nop 0
	global_load_lds_dwordx4 v77, s[98:99]
	s_add_u32 s90, s90, 0x80
	s_addc_u32 s91, s91, 0
	s_add_u32 s92, s92, 0x80
	s_addc_u32 s93, s93, 0
	s_add_u32 s98, s98, 0x80
	s_addc_u32 s99, s99, 0
	s_and_b64 vcc, exec, s[6:7]
	s_cbranch_vccnz .Lgp1_nosleep
	s_sleep 8

.Lgp1_last:
	v_mfma_f32_16x16x32_bf16 v[56:59], v[216:219], v[184:187], v[56:59]
	v_mfma_f32_16x16x32_bf16 v[116:119], v[248:251], v[184:187], v[116:119]
	v_mfma_f32_16x16x32_bf16 v[48:51], v[220:223], v[184:187], v[48:51]
	v_mfma_f32_16x16x32_bf16 v[120:123], v[252:255], v[184:187], v[120:123]
	v_mfma_f32_16x16x32_bf16 v[60:63], v[224:227], v[184:187], v[60:63]
	v_mfma_f32_16x16x32_bf16 v[124:127], v[68:71], v[184:187], v[124:127]
	v_mfma_f32_16x16x32_bf16 v[52:55], v[228:231], v[184:187], v[52:55]
	v_mfma_f32_16x16x32_bf16 v[128:131], v[72:75], v[184:187], v[128:131]
	v_mfma_f32_16x16x32_bf16 v[40:43], v[216:219], v[188:191], v[40:43]
	v_mfma_f32_16x16x32_bf16 v[132:135], v[248:251], v[188:191], v[132:135]
	v_mfma_f32_16x16x32_bf16 v[32:35], v[220:223], v[188:191], v[32:35]
	v_mfma_f32_16x16x32_bf16 v[136:139], v[252:255], v[188:191], v[136:139]
	v_mfma_f32_16x16x32_bf16 v[44:47], v[224:227], v[188:191], v[44:47]
	v_mfma_f32_16x16x32_bf16 v[140:143], v[68:71], v[188:191], v[140:143]
	v_mfma_f32_16x16x32_bf16 v[36:39], v[228:231], v[188:191], v[36:39]
	v_mfma_f32_16x16x32_bf16 v[144:147], v[72:75], v[188:191], v[144:147]
	v_mfma_f32_16x16x32_bf16 v[24:27], v[216:219], v[192:195], v[24:27]
	v_mfma_f32_16x16x32_bf16 v[148:151], v[248:251], v[192:195], v[148:151]
	v_mfma_f32_16x16x32_bf16 v[16:19], v[220:223], v[192:195], v[16:19]
	v_mfma_f32_16x16x32_bf16 v[152:155], v[252:255], v[192:195], v[152:155]
	v_mfma_f32_16x16x32_bf16 v[28:31], v[224:227], v[192:195], v[28:31]
	v_mfma_f32_16x16x32_bf16 v[156:159], v[68:71], v[192:195], v[156:159]
	v_mfma_f32_16x16x32_bf16 v[20:23], v[228:231], v[192:195], v[20:23]
	v_mfma_f32_16x16x32_bf16 v[160:163], v[72:75], v[192:195], v[160:163]
	v_mfma_f32_16x16x32_bf16 v[8:11], v[216:219], v[196:199], v[8:11]
	v_mfma_f32_16x16x32_bf16 v[164:167], v[248:251], v[196:199], v[164:167]
	v_mfma_f32_16x16x32_bf16 v[0:3], v[220:223], v[196:199], v[0:3]
	v_mfma_f32_16x16x32_bf16 v[172:175], v[252:255], v[196:199], v[172:175]
	v_mfma_f32_16x16x32_bf16 v[12:15], v[224:227], v[196:199], v[12:15]
	v_mfma_f32_16x16x32_bf16 v[176:179], v[68:71], v[196:199], v[176:179]
	v_mfma_f32_16x16x32_bf16 v[4:7], v[228:231], v[196:199], v[4:7]
	v_mfma_f32_16x16x32_bf16 v[180:183], v[72:75], v[196:199], v[180:183]
	v_mfma_f32_16x16x32_bf16 v[56:59], v[232:235], v[200:203], v[56:59]
	v_mfma_f32_16x16x32_bf16 v[116:119], v[96:99], v[200:203], v[116:119]
	v_mfma_f32_16x16x32_bf16 v[48:51], v[236:239], v[200:203], v[48:51]
	v_mfma_f32_16x16x32_bf16 v[120:123], v[100:103], v[200:203], v[120:123]
	v_mfma_f32_16x16x32_bf16 v[60:63], v[240:243], v[200:203], v[60:63]
	v_mfma_f32_16x16x32_bf16 v[124:127], v[104:107], v[200:203], v[124:127]
	v_mfma_f32_16x16x32_bf16 v[52:55], v[244:247], v[200:203], v[52:55]
	v_mfma_f32_16x16x32_bf16 v[128:131], v[112:115], v[200:203], v[128:131]
	v_mfma_f32_16x16x32_bf16 v[40:43], v[232:235], v[204:207], v[40:43]
	v_mfma_f32_16x16x32_bf16 v[132:135], v[96:99], v[204:207], v[132:135]
	v_mfma_f32_16x16x32_bf16 v[32:35], v[236:239], v[204:207], v[32:35]
	v_mfma_f32_16x16x32_bf16 v[136:139], v[100:103], v[204:207], v[136:139]
	v_mfma_f32_16x16x32_bf16 v[44:47], v[240:243], v[204:207], v[44:47]
	v_mfma_f32_16x16x32_bf16 v[140:143], v[104:107], v[204:207], v[140:143]
	v_mfma_f32_16x16x32_bf16 v[36:39], v[244:247], v[204:207], v[36:39]
	v_mfma_f32_16x16x32_bf16 v[144:147], v[112:115], v[204:207], v[144:147]
	v_mfma_f32_16x16x32_bf16 v[24:27], v[232:235], v[208:211], v[24:27]
	v_mfma_f32_16x16x32_bf16 v[148:151], v[96:99], v[208:211], v[148:151]
	v_mfma_f32_16x16x32_bf16 v[16:19], v[236:239], v[208:211], v[16:19]
	v_mfma_f32_16x16x32_bf16 v[152:155], v[100:103], v[208:211], v[152:155]
	v_mfma_f32_16x16x32_bf16 v[28:31], v[240:243], v[208:211], v[28:31]
	v_mfma_f32_16x16x32_bf16 v[156:159], v[104:107], v[208:211], v[156:159]
	v_mfma_f32_16x16x32_bf16 v[20:23], v[244:247], v[208:211], v[20:23]
	v_mfma_f32_16x16x32_bf16 v[160:163], v[112:115], v[208:211], v[160:163]
	v_mfma_f32_16x16x32_bf16 v[8:11], v[232:235], v[212:215], v[8:11]
	v_mfma_f32_16x16x32_bf16 v[164:167], v[96:99], v[212:215], v[164:167]
	v_mfma_f32_16x16x32_bf16 v[0:3], v[236:239], v[212:215], v[0:3]
	v_mfma_f32_16x16x32_bf16 v[172:175], v[100:103], v[212:215], v[172:175]
	v_mfma_f32_16x16x32_bf16 v[12:15], v[240:243], v[212:215], v[12:15]
	v_mfma_f32_16x16x32_bf16 v[176:179], v[104:107], v[212:215], v[176:179]
	v_mfma_f32_16x16x32_bf16 v[4:7], v[244:247], v[212:215], v[4:7]
	v_mfma_f32_16x16x32_bf16 v[180:183], v[112:115], v[212:215], v[180:183]
	s_nop 7
	s_nop 3
	v_lshrrev_b32_e32 v212, 1, v168
	v_and_b32_e32 v212, 0x1c0, v212
	v_and_b32_e32 v213, 15, v168
	v_or_b32_e32 v212, v212, v213
	v_lshl_add_u32 v212, s60, 7, v212
	v_lshlrev_b32_e32 v212, 11, v212
	v_bfe_u32 v213, v168, 4, 2
	v_lshlrev_b32_e32 v209, 3, v213
	v_and_b32_e32 v213, 1, v213
	v_mul_u32_u24_e32 v213, 24, v213
	v_add3_u32 v212, v212, v213, v209
	v_bfe_u32 v213, v168, 6, 1
	s_cmp_lt_u32 s58, 16
	s_cbranch_scc1 .Lep1a_B
	s_sub_u32 s87, s58, 16
	s_lshr_b32 s88, s87, 3
	s_and_b32 s87, s87, 7
	s_lshl_b32 s89, s88, 3
	s_add_u32 s89, s89, 0xe0
	s_load_dwordx2 s[84:85], s[0:1], s89
	s_cmp_eq_u32 s88, 1
	s_cselect_b32 s88, 1, 0
	s_cmp_lt_u32 s87, 4
	s_cselect_b32 s88, s88, 0
	s_mov_b32 s86, 1.0
	s_cmp_eq_u32 s88, 1
	s_cselect_b32 s86, 0x3db504f3, s86
	s_lshl_b32 s87, s87, 8
	v_lshl_add_u32 v208, v213, 7, v212
	v_add_u32_e32 v208, s87, v208
	v_add_u32_e32 v209, 0x8000, v208
	v_add_u32_e32 v210, 0x10000, v208
	v_add_u32_e32 v211, 0x18000, v208
	s_waitcnt lgkmcnt(0)
	v_mul_f32_e32 v184, s86, v56
	v_mul_f32_e32 v185, s86, v57
	v_mul_f32_e32 v186, s86, v58
	v_mul_f32_e32 v187, s86, v59
	v_mul_f32_e32 v188, s86, v48
	v_mul_f32_e32 v189, s86, v49
	v_mul_f32_e32 v190, s86, v50
	v_mul_f32_e32 v191, s86, v51
	v_and_b32_sdwa v192, v184, v110 dst_sel:DWORD dst_unused:UNUSED_PAD src0_sel:WORD_1 src1_sel:DWORD
	v_and_b32_sdwa v193, v185, v110 dst_sel:DWORD dst_unused:UNUSED_PAD src0_sel:WORD_1 src1_sel:DWORD
	v_and_b32_sdwa v194, v186, v110 dst_sel:DWORD dst_unused:UNUSED_PAD src0_sel:WORD_1 src1_sel:DWORD
	v_and_b32_sdwa v195, v187, v110 dst_sel:DWORD dst_unused:UNUSED_PAD src0_sel:WORD_1 src1_sel:DWORD
	v_and_b32_sdwa v196, v188, v110 dst_sel:DWORD dst_unused:UNUSED_PAD src0_sel:WORD_1 src1_sel:DWORD
	v_and_b32_sdwa v197, v189, v110 dst_sel:DWORD dst_unused:UNUSED_PAD src0_sel:WORD_1 src1_sel:DWORD
	v_and_b32_sdwa v198, v190, v110 dst_sel:DWORD dst_unused:UNUSED_PAD src0_sel:WORD_1 src1_sel:DWORD
	v_and_b32_sdwa v199, v191, v110 dst_sel:DWORD dst_unused:UNUSED_PAD src0_sel:WORD_1 src1_sel:DWORD
	v_add3_u32 v184, v184, v192, s69
	v_add3_u32 v185, v185, v193, s69
	v_add3_u32 v186, v186, v194, s69
	v_add3_u32 v187, v187, v195, s69
	v_add3_u32 v188, v188, v196, s69
	v_add3_u32 v189, v189, v197, s69
	v_add3_u32 v190, v190, v198, s69
	v_add3_u32 v191, v191, v199, s69
	v_and_b32_e32 v185, 0xffff0000, v185
	v_and_b32_e32 v187, 0xffff0000, v187
	v_and_b32_e32 v189, 0xffff0000, v189
	v_and_b32_e32 v191, 0xffff0000, v191
	v_or_b32_sdwa v200, v185, v184 dst_sel:DWORD dst_unused:UNUSED_PAD src0_sel:DWORD src1_sel:WORD_1
	v_or_b32_sdwa v201, v187, v186 dst_sel:DWORD dst_unused:UNUSED_PAD src0_sel:DWORD src1_sel:WORD_1
	v_or_b32_sdwa v202, v189, v188 dst_sel:DWORD dst_unused:UNUSED_PAD src0_sel:DWORD src1_sel:WORD_1
	v_or_b32_sdwa v203, v191, v190 dst_sel:DWORD dst_unused:UNUSED_PAD src0_sel:DWORD src1_sel:WORD_1
	s_nop 1
	v_permlane16_swap_b32_e32 v200, v202
	v_permlane16_swap_b32_e32 v201, v203
	global_store_dwordx4 v208, v[200:203], s[84:85]
	v_mul_f32_e32 v184, s86, v60
	v_mul_f32_e32 v185, s86, v61
	v_mul_f32_e32 v186, s86, v62
	v_mul_f32_e32 v187, s86, v63
	v_mul_f32_e32 v188, s86, v52
	v_mul_f32_e32 v189, s86, v53
	v_mul_f32_e32 v190, s86, v54
	v_mul_f32_e32 v191, s86, v55
	v_and_b32_sdwa v192, v184, v110 dst_sel:DWORD dst_unused:UNUSED_PAD src0_sel:WORD_1 src1_sel:DWORD
	v_and_b32_sdwa v193, v185, v110 dst_sel:DWORD dst_unused:UNUSED_PAD src0_sel:WORD_1 src1_sel:DWORD
	v_and_b32_sdwa v194, v186, v110 dst_sel:DWORD dst_unused:UNUSED_PAD src0_sel:WORD_1 src1_sel:DWORD
	v_and_b32_sdwa v195, v187, v110 dst_sel:DWORD dst_unused:UNUSED_PAD src0_sel:WORD_1 src1_sel:DWORD
	v_and_b32_sdwa v196, v188, v110 dst_sel:DWORD dst_unused:UNUSED_PAD src0_sel:WORD_1 src1_sel:DWORD
	v_and_b32_sdwa v197, v189, v110 dst_sel:DWORD dst_unused:UNUSED_PAD src0_sel:WORD_1 src1_sel:DWORD
	v_and_b32_sdwa v198, v190, v110 dst_sel:DWORD dst_unused:UNUSED_PAD src0_sel:WORD_1 src1_sel:DWORD
	v_and_b32_sdwa v199, v191, v110 dst_sel:DWORD dst_unused:UNUSED_PAD src0_sel:WORD_1 src1_sel:DWORD
	v_add3_u32 v184, v184, v192, s69
	v_add3_u32 v185, v185, v193, s69
	v_add3_u32 v186, v186, v194, s69
	v_add3_u32 v187, v187, v195, s69
	v_add3_u32 v188, v188, v196, s69
	v_add3_u32 v189, v189, v197, s69
	v_add3_u32 v190, v190, v198, s69
	v_add3_u32 v191, v191, v199, s69
	v_and_b32_e32 v185, 0xffff0000, v185
	v_and_b32_e32 v187, 0xffff0000, v187
	v_and_b32_e32 v189, 0xffff0000, v189
	v_and_b32_e32 v191, 0xffff0000, v191
	v_or_b32_sdwa v204, v185, v184 dst_sel:DWORD dst_unused:UNUSED_PAD src0_sel:DWORD src1_sel:WORD_1
	v_or_b32_sdwa v205, v187, v186 dst_sel:DWORD dst_unused:UNUSED_PAD src0_sel:DWORD src1_sel:WORD_1
	v_or_b32_sdwa v206, v189, v188 dst_sel:DWORD dst_unused:UNUSED_PAD src0_sel:DWORD src1_sel:WORD_1
	v_or_b32_sdwa v207, v191, v190 dst_sel:DWORD dst_unused:UNUSED_PAD src0_sel:DWORD src1_sel:WORD_1
	s_nop 1
	v_permlane16_swap_b32_e32 v204, v206
	v_permlane16_swap_b32_e32 v205, v207
	global_store_dwordx4 v208, v[204:207], s[84:85] offset:64
	v_mul_f32_e32 v184, s86, v40
	v_mul_f32_e32 v185, s86, v41
	v_mul_f32_e32 v186, s86, v42
	v_mul_f32_e32 v187, s86, v43
	v_mul_f32_e32 v188, s86, v32
	v_mul_f32_e32 v189, s86, v33
	v_mul_f32_e32 v190, s86, v34
	v_mul_f32_e32 v191, s86, v35
	v_and_b32_sdwa v192, v184, v110 dst_sel:DWORD dst_unused:UNUSED_PAD src0_sel:WORD_1 src1_sel:DWORD
	v_and_b32_sdwa v193, v185, v110 dst_sel:DWORD dst_unused:UNUSED_PAD src0_sel:WORD_1 src1_sel:DWORD
	v_and_b32_sdwa v194, v186, v110 dst_sel:DWORD dst_unused:UNUSED_PAD src0_sel:WORD_1 src1_sel:DWORD
	v_and_b32_sdwa v195, v187, v110 dst_sel:DWORD dst_unused:UNUSED_PAD src0_sel:WORD_1 src1_sel:DWORD
	v_and_b32_sdwa v196, v188, v110 dst_sel:DWORD dst_unused:UNUSED_PAD src0_sel:WORD_1 src1_sel:DWORD
	v_and_b32_sdwa v197, v189, v110 dst_sel:DWORD dst_unused:UNUSED_PAD src0_sel:WORD_1 src1_sel:DWORD
	v_and_b32_sdwa v198, v190, v110 dst_sel:DWORD dst_unused:UNUSED_PAD src0_sel:WORD_1 src1_sel:DWORD
	v_and_b32_sdwa v199, v191, v110 dst_sel:DWORD dst_unused:UNUSED_PAD src0_sel:WORD_1 src1_sel:DWORD
	v_add3_u32 v184, v184, v192, s69
	v_add3_u32 v185, v185, v193, s69
	v_add3_u32 v186, v186, v194, s69
	v_add3_u32 v187, v187, v195, s69
	v_add3_u32 v188, v188, v196, s69
	v_add3_u32 v189, v189, v197, s69
	v_add3_u32 v190, v190, v198, s69
	v_add3_u32 v191, v191, v199, s69
	v_and_b32_e32 v185, 0xffff0000, v185
	v_and_b32_e32 v187, 0xffff0000, v187
	v_and_b32_e32 v189, 0xffff0000, v189
	v_and_b32_e32 v191, 0xffff0000, v191
	v_or_b32_sdwa v200, v185, v184 dst_sel:DWORD dst_unused:UNUSED_PAD src0_sel:DWORD src1_sel:WORD_1
	v_or_b32_sdwa v201, v187, v186 dst_sel:DWORD dst_unused:UNUSED_PAD src0_sel:DWORD src1_sel:WORD_1
	v_or_b32_sdwa v202, v189, v188 dst_sel:DWORD dst_unused:UNUSED_PAD src0_sel:DWORD src1_sel:WORD_1
	v_or_b32_sdwa v203, v191, v190 dst_sel:DWORD dst_unused:UNUSED_PAD src0_sel:DWORD src1_sel:WORD_1
	s_nop 1
	v_permlane16_swap_b32_e32 v200, v202
	v_permlane16_swap_b32_e32 v201, v203
	global_store_dwordx4 v209, v[200:203], s[84:85]
	v_mul_f32_e32 v184, s86, v44
	v_mul_f32_e32 v185, s86, v45
	v_mul_f32_e32 v186, s86, v46
	v_mul_f32_e32 v187, s86, v47
	v_mul_f32_e32 v188, s86, v36
	v_mul_f32_e32 v189, s86, v37
	v_mul_f32_e32 v190, s86, v38
	v_mul_f32_e32 v191, s86, v39
	v_and_b32_sdwa v192, v184, v110 dst_sel:DWORD dst_unused:UNUSED_PAD src0_sel:WORD_1 src1_sel:DWORD
	v_and_b32_sdwa v193, v185, v110 dst_sel:DWORD dst_unused:UNUSED_PAD src0_sel:WORD_1 src1_sel:DWORD
	v_and_b32_sdwa v194, v186, v110 dst_sel:DWORD dst_unused:UNUSED_PAD src0_sel:WORD_1 src1_sel:DWORD
	v_and_b32_sdwa v195, v187, v110 dst_sel:DWORD dst_unused:UNUSED_PAD src0_sel:WORD_1 src1_sel:DWORD
	v_and_b32_sdwa v196, v188, v110 dst_sel:DWORD dst_unused:UNUSED_PAD src0_sel:WORD_1 src1_sel:DWORD
	v_and_b32_sdwa v197, v189, v110 dst_sel:DWORD dst_unused:UNUSED_PAD src0_sel:WORD_1 src1_sel:DWORD
	v_and_b32_sdwa v198, v190, v110 dst_sel:DWORD dst_unused:UNUSED_PAD src0_sel:WORD_1 src1_sel:DWORD
	v_and_b32_sdwa v199, v191, v110 dst_sel:DWORD dst_unused:UNUSED_PAD src0_sel:WORD_1 src1_sel:DWORD
	v_add3_u32 v184, v184, v192, s69
	v_add3_u32 v185, v185, v193, s69
	v_add3_u32 v186, v186, v194, s69
	v_add3_u32 v187, v187, v195, s69
	v_add3_u32 v188, v188, v196, s69
	v_add3_u32 v189, v189, v197, s69
	v_add3_u32 v190, v190, v198, s69
	v_add3_u32 v191, v191, v199, s69
	v_and_b32_e32 v185, 0xffff0000, v185
	v_and_b32_e32 v187, 0xffff0000, v187
	v_and_b32_e32 v189, 0xffff0000, v189
	v_and_b32_e32 v191, 0xffff0000, v191
	v_or_b32_sdwa v204, v185, v184 dst_sel:DWORD dst_unused:UNUSED_PAD src0_sel:DWORD src1_sel:WORD_1
	v_or_b32_sdwa v205, v187, v186 dst_sel:DWORD dst_unused:UNUSED_PAD src0_sel:DWORD src1_sel:WORD_1
	v_or_b32_sdwa v206, v189, v188 dst_sel:DWORD dst_unused:UNUSED_PAD src0_sel:DWORD src1_sel:WORD_1
	v_or_b32_sdwa v207, v191, v190 dst_sel:DWORD dst_unused:UNUSED_PAD src0_sel:DWORD src1_sel:WORD_1
	s_nop 1
	v_permlane16_swap_b32_e32 v204, v206
	v_permlane16_swap_b32_e32 v205, v207
	global_store_dwordx4 v209, v[204:207], s[84:85] offset:64
	v_mul_f32_e32 v184, s86, v24
	v_mul_f32_e32 v185, s86, v25
	v_mul_f32_e32 v186, s86, v26
	v_mul_f32_e32 v187, s86, v27
	v_mul_f32_e32 v188, s86, v16
	v_mul_f32_e32 v189, s86, v17
	v_mul_f32_e32 v190, s86, v18
	v_mul_f32_e32 v191, s86, v19
	v_and_b32_sdwa v192, v184, v110 dst_sel:DWORD dst_unused:UNUSED_PAD src0_sel:WORD_1 src1_sel:DWORD
	v_and_b32_sdwa v193, v185, v110 dst_sel:DWORD dst_unused:UNUSED_PAD src0_sel:WORD_1 src1_sel:DWORD
	v_and_b32_sdwa v194, v186, v110 dst_sel:DWORD dst_unused:UNUSED_PAD src0_sel:WORD_1 src1_sel:DWORD
	v_and_b32_sdwa v195, v187, v110 dst_sel:DWORD dst_unused:UNUSED_PAD src0_sel:WORD_1 src1_sel:DWORD
	v_and_b32_sdwa v196, v188, v110 dst_sel:DWORD dst_unused:UNUSED_PAD src0_sel:WORD_1 src1_sel:DWORD
	v_and_b32_sdwa v197, v189, v110 dst_sel:DWORD dst_unused:UNUSED_PAD src0_sel:WORD_1 src1_sel:DWORD
	v_and_b32_sdwa v198, v190, v110 dst_sel:DWORD dst_unused:UNUSED_PAD src0_sel:WORD_1 src1_sel:DWORD
	v_and_b32_sdwa v199, v191, v110 dst_sel:DWORD dst_unused:UNUSED_PAD src0_sel:WORD_1 src1_sel:DWORD
	v_add3_u32 v184, v184, v192, s69
	v_add3_u32 v185, v185, v193, s69
	v_add3_u32 v186, v186, v194, s69
	v_add3_u32 v187, v187, v195, s69
	v_add3_u32 v188, v188, v196, s69
	v_add3_u32 v189, v189, v197, s69
	v_add3_u32 v190, v190, v198, s69
	v_add3_u32 v191, v191, v199, s69
	v_and_b32_e32 v185, 0xffff0000, v185
	v_and_b32_e32 v187, 0xffff0000, v187
	v_and_b32_e32 v189, 0xffff0000, v189
	v_and_b32_e32 v191, 0xffff0000, v191
	v_or_b32_sdwa v200, v185, v184 dst_sel:DWORD dst_unused:UNUSED_PAD src0_sel:DWORD src1_sel:WORD_1
	v_or_b32_sdwa v201, v187, v186 dst_sel:DWORD dst_unused:UNUSED_PAD src0_sel:DWORD src1_sel:WORD_1
	v_or_b32_sdwa v202, v189, v188 dst_sel:DWORD dst_unused:UNUSED_PAD src0_sel:DWORD src1_sel:WORD_1
	v_or_b32_sdwa v203, v191, v190 dst_sel:DWORD dst_unused:UNUSED_PAD src0_sel:DWORD src1_sel:WORD_1
	s_nop 1
	v_permlane16_swap_b32_e32 v200, v202
	v_permlane16_swap_b32_e32 v201, v203
	global_store_dwordx4 v210, v[200:203], s[84:85]
	v_mul_f32_e32 v184, s86, v28
	v_mul_f32_e32 v185, s86, v29
	v_mul_f32_e32 v186, s86, v30
	v_mul_f32_e32 v187, s86, v31
	v_mul_f32_e32 v188, s86, v20
	v_mul_f32_e32 v189, s86, v21
	v_mul_f32_e32 v190, s86, v22
	v_mul_f32_e32 v191, s86, v23
	v_and_b32_sdwa v192, v184, v110 dst_sel:DWORD dst_unused:UNUSED_PAD src0_sel:WORD_1 src1_sel:DWORD
	v_and_b32_sdwa v193, v185, v110 dst_sel:DWORD dst_unused:UNUSED_PAD src0_sel:WORD_1 src1_sel:DWORD
	v_and_b32_sdwa v194, v186, v110 dst_sel:DWORD dst_unused:UNUSED_PAD src0_sel:WORD_1 src1_sel:DWORD
	v_and_b32_sdwa v195, v187, v110 dst_sel:DWORD dst_unused:UNUSED_PAD src0_sel:WORD_1 src1_sel:DWORD
	v_and_b32_sdwa v196, v188, v110 dst_sel:DWORD dst_unused:UNUSED_PAD src0_sel:WORD_1 src1_sel:DWORD
	v_and_b32_sdwa v197, v189, v110 dst_sel:DWORD dst_unused:UNUSED_PAD src0_sel:WORD_1 src1_sel:DWORD
	v_and_b32_sdwa v198, v190, v110 dst_sel:DWORD dst_unused:UNUSED_PAD src0_sel:WORD_1 src1_sel:DWORD
	v_and_b32_sdwa v199, v191, v110 dst_sel:DWORD dst_unused:UNUSED_PAD src0_sel:WORD_1 src1_sel:DWORD
	v_add3_u32 v184, v184, v192, s69
	v_add3_u32 v185, v185, v193, s69
	v_add3_u32 v186, v186, v194, s69
	v_add3_u32 v187, v187, v195, s69
	v_add3_u32 v188, v188, v196, s69
	v_add3_u32 v189, v189, v197, s69
	v_add3_u32 v190, v190, v198, s69
	v_add3_u32 v191, v191, v199, s69
	v_and_b32_e32 v185, 0xffff0000, v185
	v_and_b32_e32 v187, 0xffff0000, v187
	v_and_b32_e32 v189, 0xffff0000, v189
	v_and_b32_e32 v191, 0xffff0000, v191
	v_or_b32_sdwa v204, v185, v184 dst_sel:DWORD dst_unused:UNUSED_PAD src0_sel:DWORD src1_sel:WORD_1
	v_or_b32_sdwa v205, v187, v186 dst_sel:DWORD dst_unused:UNUSED_PAD src0_sel:DWORD src1_sel:WORD_1
	v_or_b32_sdwa v206, v189, v188 dst_sel:DWORD dst_unused:UNUSED_PAD src0_sel:DWORD src1_sel:WORD_1
	v_or_b32_sdwa v207, v191, v190 dst_sel:DWORD dst_unused:UNUSED_PAD src0_sel:DWORD src1_sel:WORD_1
	s_nop 1
	v_permlane16_swap_b32_e32 v204, v206
	v_permlane16_swap_b32_e32 v205, v207
	global_store_dwordx4 v210, v[204:207], s[84:85] offset:64
	v_mul_f32_e32 v184, s86, v8
	v_mul_f32_e32 v185, s86, v9
	v_mul_f32_e32 v186, s86, v10
	v_mul_f32_e32 v187, s86, v11
	v_mul_f32_e32 v188, s86, v0
	v_mul_f32_e32 v189, s86, v1
	v_mul_f32_e32 v190, s86, v2
	v_mul_f32_e32 v191, s86, v3
	v_and_b32_sdwa v192, v184, v110 dst_sel:DWORD dst_unused:UNUSED_PAD src0_sel:WORD_1 src1_sel:DWORD
	v_and_b32_sdwa v193, v185, v110 dst_sel:DWORD dst_unused:UNUSED_PAD src0_sel:WORD_1 src1_sel:DWORD
	v_and_b32_sdwa v194, v186, v110 dst_sel:DWORD dst_unused:UNUSED_PAD src0_sel:WORD_1 src1_sel:DWORD
	v_and_b32_sdwa v195, v187, v110 dst_sel:DWORD dst_unused:UNUSED_PAD src0_sel:WORD_1 src1_sel:DWORD
	v_and_b32_sdwa v196, v188, v110 dst_sel:DWORD dst_unused:UNUSED_PAD src0_sel:WORD_1 src1_sel:DWORD
	v_and_b32_sdwa v197, v189, v110 dst_sel:DWORD dst_unused:UNUSED_PAD src0_sel:WORD_1 src1_sel:DWORD
	v_and_b32_sdwa v198, v190, v110 dst_sel:DWORD dst_unused:UNUSED_PAD src0_sel:WORD_1 src1_sel:DWORD
	v_and_b32_sdwa v199, v191, v110 dst_sel:DWORD dst_unused:UNUSED_PAD src0_sel:WORD_1 src1_sel:DWORD
	v_add3_u32 v184, v184, v192, s69
	v_add3_u32 v185, v185, v193, s69
	v_add3_u32 v186, v186, v194, s69
	v_add3_u32 v187, v187, v195, s69
	v_add3_u32 v188, v188, v196, s69
	v_add3_u32 v189, v189, v197, s69
	v_add3_u32 v190, v190, v198, s69
	v_add3_u32 v191, v191, v199, s69
	v_and_b32_e32 v185, 0xffff0000, v185
	v_and_b32_e32 v187, 0xffff0000, v187
	v_and_b32_e32 v189, 0xffff0000, v189
	v_and_b32_e32 v191, 0xffff0000, v191
	v_or_b32_sdwa v200, v185, v184 dst_sel:DWORD dst_unused:UNUSED_PAD src0_sel:DWORD src1_sel:WORD_1
	v_or_b32_sdwa v201, v187, v186 dst_sel:DWORD dst_unused:UNUSED_PAD src0_sel:DWORD src1_sel:WORD_1
	v_or_b32_sdwa v202, v189, v188 dst_sel:DWORD dst_unused:UNUSED_PAD src0_sel:DWORD src1_sel:WORD_1
	v_or_b32_sdwa v203, v191, v190 dst_sel:DWORD dst_unused:UNUSED_PAD src0_sel:DWORD src1_sel:WORD_1
	s_nop 1
	v_permlane16_swap_b32_e32 v200, v202
	v_permlane16_swap_b32_e32 v201, v203
	global_store_dwordx4 v211, v[200:203], s[84:85]
	v_mul_f32_e32 v184, s86, v12
	v_mul_f32_e32 v185, s86, v13
	v_mul_f32_e32 v186, s86, v14
	v_mul_f32_e32 v187, s86, v15
	v_mul_f32_e32 v188, s86, v4
	v_mul_f32_e32 v189, s86, v5
	v_mul_f32_e32 v190, s86, v6
	v_mul_f32_e32 v191, s86, v7
	v_and_b32_sdwa v192, v184, v110 dst_sel:DWORD dst_unused:UNUSED_PAD src0_sel:WORD_1 src1_sel:DWORD
	v_and_b32_sdwa v193, v185, v110 dst_sel:DWORD dst_unused:UNUSED_PAD src0_sel:WORD_1 src1_sel:DWORD
	v_and_b32_sdwa v194, v186, v110 dst_sel:DWORD dst_unused:UNUSED_PAD src0_sel:WORD_1 src1_sel:DWORD
	v_and_b32_sdwa v195, v187, v110 dst_sel:DWORD dst_unused:UNUSED_PAD src0_sel:WORD_1 src1_sel:DWORD
	v_and_b32_sdwa v196, v188, v110 dst_sel:DWORD dst_unused:UNUSED_PAD src0_sel:WORD_1 src1_sel:DWORD
	v_and_b32_sdwa v197, v189, v110 dst_sel:DWORD dst_unused:UNUSED_PAD src0_sel:WORD_1 src1_sel:DWORD
	v_and_b32_sdwa v198, v190, v110 dst_sel:DWORD dst_unused:UNUSED_PAD src0_sel:WORD_1 src1_sel:DWORD
	v_and_b32_sdwa v199, v191, v110 dst_sel:DWORD dst_unused:UNUSED_PAD src0_sel:WORD_1 src1_sel:DWORD
	v_add3_u32 v184, v184, v192, s69
	v_add3_u32 v185, v185, v193, s69
	v_add3_u32 v186, v186, v194, s69
	v_add3_u32 v187, v187, v195, s69
	v_add3_u32 v188, v188, v196, s69
	v_add3_u32 v189, v189, v197, s69
	v_add3_u32 v190, v190, v198, s69
	v_add3_u32 v191, v191, v199, s69
	v_and_b32_e32 v185, 0xffff0000, v185
	v_and_b32_e32 v187, 0xffff0000, v187
	v_and_b32_e32 v189, 0xffff0000, v189
	v_and_b32_e32 v191, 0xffff0000, v191
	v_or_b32_sdwa v204, v185, v184 dst_sel:DWORD dst_unused:UNUSED_PAD src0_sel:DWORD src1_sel:WORD_1
	v_or_b32_sdwa v205, v187, v186 dst_sel:DWORD dst_unused:UNUSED_PAD src0_sel:DWORD src1_sel:WORD_1
	v_or_b32_sdwa v206, v189, v188 dst_sel:DWORD dst_unused:UNUSED_PAD src0_sel:DWORD src1_sel:WORD_1
	v_or_b32_sdwa v207, v191, v190 dst_sel:DWORD dst_unused:UNUSED_PAD src0_sel:DWORD src1_sel:WORD_1
	s_nop 1
	v_permlane16_swap_b32_e32 v204, v206
	v_permlane16_swap_b32_e32 v205, v207
	global_store_dwordx4 v211, v[204:207], s[84:85] offset:64
	s_branch .Lep1a_done
.Lep1a_B:
	s_load_dwordx2 s[84:85], s[0:1], 0xd8
	s_lshl_b32 s87, s58, 7
	v_lshl_add_u32 v208, v213, 6, v212
	v_add_u32_e32 v208, s87, v208
	v_add_u32_e32 v209, 0x8000, v208
	v_add_u32_e32 v210, 0x10000, v208
	v_add_u32_e32 v211, 0x18000, v208
	s_waitcnt lgkmcnt(0)
	v_mul_f32_e32 v184, v60, v56
	v_mul_f32_e32 v185, v61, v57
	v_mul_f32_e32 v186, v62, v58
	v_mul_f32_e32 v187, v63, v59
	v_mul_f32_e32 v188, v52, v48
	v_mul_f32_e32 v189, v53, v49
	v_mul_f32_e32 v190, v54, v50
	v_mul_f32_e32 v191, v55, v51
	v_and_b32_sdwa v192, v184, v110 dst_sel:DWORD dst_unused:UNUSED_PAD src0_sel:WORD_1 src1_sel:DWORD
	v_and_b32_sdwa v193, v185, v110 dst_sel:DWORD dst_unused:UNUSED_PAD src0_sel:WORD_1 src1_sel:DWORD
	v_and_b32_sdwa v194, v186, v110 dst_sel:DWORD dst_unused:UNUSED_PAD src0_sel:WORD_1 src1_sel:DWORD
	v_and_b32_sdwa v195, v187, v110 dst_sel:DWORD dst_unused:UNUSED_PAD src0_sel:WORD_1 src1_sel:DWORD
	v_and_b32_sdwa v196, v188, v110 dst_sel:DWORD dst_unused:UNUSED_PAD src0_sel:WORD_1 src1_sel:DWORD
	v_and_b32_sdwa v197, v189, v110 dst_sel:DWORD dst_unused:UNUSED_PAD src0_sel:WORD_1 src1_sel:DWORD
	v_and_b32_sdwa v198, v190, v110 dst_sel:DWORD dst_unused:UNUSED_PAD src0_sel:WORD_1 src1_sel:DWORD
	v_and_b32_sdwa v199, v191, v110 dst_sel:DWORD dst_unused:UNUSED_PAD src0_sel:WORD_1 src1_sel:DWORD
	v_add3_u32 v184, v184, v192, s69
	v_add3_u32 v185, v185, v193, s69
	v_add3_u32 v186, v186, v194, s69
	v_add3_u32 v187, v187, v195, s69
	v_add3_u32 v188, v188, v196, s69
	v_add3_u32 v189, v189, v197, s69
	v_add3_u32 v190, v190, v198, s69
	v_add3_u32 v191, v191, v199, s69
	v_and_b32_e32 v185, 0xffff0000, v185
	v_and_b32_e32 v187, 0xffff0000, v187
	v_and_b32_e32 v189, 0xffff0000, v189
	v_and_b32_e32 v191, 0xffff0000, v191
	v_or_b32_sdwa v200, v185, v184 dst_sel:DWORD dst_unused:UNUSED_PAD src0_sel:DWORD src1_sel:WORD_1
	v_or_b32_sdwa v201, v187, v186 dst_sel:DWORD dst_unused:UNUSED_PAD src0_sel:DWORD src1_sel:WORD_1
	v_or_b32_sdwa v202, v189, v188 dst_sel:DWORD dst_unused:UNUSED_PAD src0_sel:DWORD src1_sel:WORD_1
	v_or_b32_sdwa v203, v191, v190 dst_sel:DWORD dst_unused:UNUSED_PAD src0_sel:DWORD src1_sel:WORD_1
	s_nop 1
	v_permlane16_swap_b32_e32 v200, v202
	v_permlane16_swap_b32_e32 v201, v203
	global_store_dwordx4 v208, v[200:203], s[84:85]
	v_mul_f32_e32 v184, v44, v40
	v_mul_f32_e32 v185, v45, v41
	v_mul_f32_e32 v186, v46, v42
	v_mul_f32_e32 v187, v47, v43
	v_mul_f32_e32 v188, v36, v32
	v_mul_f32_e32 v189, v37, v33
	v_mul_f32_e32 v190, v38, v34
	v_mul_f32_e32 v191, v39, v35
	v_and_b32_sdwa v192, v184, v110 dst_sel:DWORD dst_unused:UNUSED_PAD src0_sel:WORD_1 src1_sel:DWORD
	v_and_b32_sdwa v193, v185, v110 dst_sel:DWORD dst_unused:UNUSED_PAD src0_sel:WORD_1 src1_sel:DWORD
	v_and_b32_sdwa v194, v186, v110 dst_sel:DWORD dst_unused:UNUSED_PAD src0_sel:WORD_1 src1_sel:DWORD
	v_and_b32_sdwa v195, v187, v110 dst_sel:DWORD dst_unused:UNUSED_PAD src0_sel:WORD_1 src1_sel:DWORD
	v_and_b32_sdwa v196, v188, v110 dst_sel:DWORD dst_unused:UNUSED_PAD src0_sel:WORD_1 src1_sel:DWORD
	v_and_b32_sdwa v197, v189, v110 dst_sel:DWORD dst_unused:UNUSED_PAD src0_sel:WORD_1 src1_sel:DWORD
	v_and_b32_sdwa v198, v190, v110 dst_sel:DWORD dst_unused:UNUSED_PAD src0_sel:WORD_1 src1_sel:DWORD
	v_and_b32_sdwa v199, v191, v110 dst_sel:DWORD dst_unused:UNUSED_PAD src0_sel:WORD_1 src1_sel:DWORD
	v_add3_u32 v184, v184, v192, s69
	v_add3_u32 v185, v185, v193, s69
	v_add3_u32 v186, v186, v194, s69
	v_add3_u32 v187, v187, v195, s69
	v_add3_u32 v188, v188, v196, s69
	v_add3_u32 v189, v189, v197, s69
	v_add3_u32 v190, v190, v198, s69
	v_add3_u32 v191, v191, v199, s69
	v_and_b32_e32 v185, 0xffff0000, v185
	v_and_b32_e32 v187, 0xffff0000, v187
	v_and_b32_e32 v189, 0xffff0000, v189
	v_and_b32_e32 v191, 0xffff0000, v191
	v_or_b32_sdwa v204, v185, v184 dst_sel:DWORD dst_unused:UNUSED_PAD src0_sel:DWORD src1_sel:WORD_1
	v_or_b32_sdwa v205, v187, v186 dst_sel:DWORD dst_unused:UNUSED_PAD src0_sel:DWORD src1_sel:WORD_1
	v_or_b32_sdwa v206, v189, v188 dst_sel:DWORD dst_unused:UNUSED_PAD src0_sel:DWORD src1_sel:WORD_1
	v_or_b32_sdwa v207, v191, v190 dst_sel:DWORD dst_unused:UNUSED_PAD src0_sel:DWORD src1_sel:WORD_1
	s_nop 1
	v_permlane16_swap_b32_e32 v204, v206
	v_permlane16_swap_b32_e32 v205, v207
	global_store_dwordx4 v209, v[204:207], s[84:85]
	v_mul_f32_e32 v184, v28, v24
	v_mul_f32_e32 v185, v29, v25
	v_mul_f32_e32 v186, v30, v26
	v_mul_f32_e32 v187, v31, v27
	v_mul_f32_e32 v188, v20, v16
	v_mul_f32_e32 v189, v21, v17
	v_mul_f32_e32 v190, v22, v18
	v_mul_f32_e32 v191, v23, v19
	v_and_b32_sdwa v192, v184, v110 dst_sel:DWORD dst_unused:UNUSED_PAD src0_sel:WORD_1 src1_sel:DWORD
	v_and_b32_sdwa v193, v185, v110 dst_sel:DWORD dst_unused:UNUSED_PAD src0_sel:WORD_1 src1_sel:DWORD
	v_and_b32_sdwa v194, v186, v110 dst_sel:DWORD dst_unused:UNUSED_PAD src0_sel:WORD_1 src1_sel:DWORD
	v_and_b32_sdwa v195, v187, v110 dst_sel:DWORD dst_unused:UNUSED_PAD src0_sel:WORD_1 src1_sel:DWORD
	v_and_b32_sdwa v196, v188, v110 dst_sel:DWORD dst_unused:UNUSED_PAD src0_sel:WORD_1 src1_sel:DWORD
	v_and_b32_sdwa v197, v189, v110 dst_sel:DWORD dst_unused:UNUSED_PAD src0_sel:WORD_1 src1_sel:DWORD
	v_and_b32_sdwa v198, v190, v110 dst_sel:DWORD dst_unused:UNUSED_PAD src0_sel:WORD_1 src1_sel:DWORD
	v_and_b32_sdwa v199, v191, v110 dst_sel:DWORD dst_unused:UNUSED_PAD src0_sel:WORD_1 src1_sel:DWORD
	v_add3_u32 v184, v184, v192, s69
	v_add3_u32 v185, v185, v193, s69
	v_add3_u32 v186, v186, v194, s69
	v_add3_u32 v187, v187, v195, s69
	v_add3_u32 v188, v188, v196, s69
	v_add3_u32 v189, v189, v197, s69
	v_add3_u32 v190, v190, v198, s69
	v_add3_u32 v191, v191, v199, s69
	v_and_b32_e32 v185, 0xffff0000, v185
	v_and_b32_e32 v187, 0xffff0000, v187
	v_and_b32_e32 v189, 0xffff0000, v189
	v_and_b32_e32 v191, 0xffff0000, v191
	v_or_b32_sdwa v200, v185, v184 dst_sel:DWORD dst_unused:UNUSED_PAD src0_sel:DWORD src1_sel:WORD_1
	v_or_b32_sdwa v201, v187, v186 dst_sel:DWORD dst_unused:UNUSED_PAD src0_sel:DWORD src1_sel:WORD_1
	v_or_b32_sdwa v202, v189, v188 dst_sel:DWORD dst_unused:UNUSED_PAD src0_sel:DWORD src1_sel:WORD_1
	v_or_b32_sdwa v203, v191, v190 dst_sel:DWORD dst_unused:UNUSED_PAD src0_sel:DWORD src1_sel:WORD_1
	s_nop 1
	v_permlane16_swap_b32_e32 v200, v202
	v_permlane16_swap_b32_e32 v201, v203
	global_store_dwordx4 v210, v[200:203], s[84:85]
	v_mul_f32_e32 v184, v12, v8
	v_mul_f32_e32 v185, v13, v9
	v_mul_f32_e32 v186, v14, v10
	v_mul_f32_e32 v187, v15, v11
	v_mul_f32_e32 v188, v4, v0
	v_mul_f32_e32 v189, v5, v1
	v_mul_f32_e32 v190, v6, v2
	v_mul_f32_e32 v191, v7, v3
	v_and_b32_sdwa v192, v184, v110 dst_sel:DWORD dst_unused:UNUSED_PAD src0_sel:WORD_1 src1_sel:DWORD
	v_and_b32_sdwa v193, v185, v110 dst_sel:DWORD dst_unused:UNUSED_PAD src0_sel:WORD_1 src1_sel:DWORD
	v_and_b32_sdwa v194, v186, v110 dst_sel:DWORD dst_unused:UNUSED_PAD src0_sel:WORD_1 src1_sel:DWORD
	v_and_b32_sdwa v195, v187, v110 dst_sel:DWORD dst_unused:UNUSED_PAD src0_sel:WORD_1 src1_sel:DWORD
	v_and_b32_sdwa v196, v188, v110 dst_sel:DWORD dst_unused:UNUSED_PAD src0_sel:WORD_1 src1_sel:DWORD
	v_and_b32_sdwa v197, v189, v110 dst_sel:DWORD dst_unused:UNUSED_PAD src0_sel:WORD_1 src1_sel:DWORD
	v_and_b32_sdwa v198, v190, v110 dst_sel:DWORD dst_unused:UNUSED_PAD src0_sel:WORD_1 src1_sel:DWORD
	v_and_b32_sdwa v199, v191, v110 dst_sel:DWORD dst_unused:UNUSED_PAD src0_sel:WORD_1 src1_sel:DWORD
	v_add3_u32 v184, v184, v192, s69
	v_add3_u32 v185, v185, v193, s69
	v_add3_u32 v186, v186, v194, s69
	v_add3_u32 v187, v187, v195, s69
	v_add3_u32 v188, v188, v196, s69
	v_add3_u32 v189, v189, v197, s69
	v_add3_u32 v190, v190, v198, s69
	v_add3_u32 v191, v191, v199, s69
	v_and_b32_e32 v185, 0xffff0000, v185
	v_and_b32_e32 v187, 0xffff0000, v187
	v_and_b32_e32 v189, 0xffff0000, v189
	v_and_b32_e32 v191, 0xffff0000, v191
	v_or_b32_sdwa v204, v185, v184 dst_sel:DWORD dst_unused:UNUSED_PAD src0_sel:DWORD src1_sel:WORD_1
	v_or_b32_sdwa v205, v187, v186 dst_sel:DWORD dst_unused:UNUSED_PAD src0_sel:DWORD src1_sel:WORD_1
	v_or_b32_sdwa v206, v189, v188 dst_sel:DWORD dst_unused:UNUSED_PAD src0_sel:DWORD src1_sel:WORD_1
	v_or_b32_sdwa v207, v191, v190 dst_sel:DWORD dst_unused:UNUSED_PAD src0_sel:DWORD src1_sel:WORD_1
	s_nop 1
	v_permlane16_swap_b32_e32 v204, v206
	v_permlane16_swap_b32_e32 v205, v207
	global_store_dwordx4 v211, v[204:207], s[84:85]
.Lep1a_done:
	s_cmp_eq_u32 s95, 1
	s_cbranch_scc0 .Lgp1_single
	v_lshrrev_b32_e32 v212, 1, v168
	v_and_b32_e32 v212, 0x1c0, v212
	v_and_b32_e32 v213, 15, v168
	v_or_b32_e32 v212, v212, v213
	v_lshl_add_u32 v212, s60, 7, v212
	v_lshlrev_b32_e32 v212, 11, v212
	v_bfe_u32 v213, v168, 4, 2
	v_lshlrev_b32_e32 v209, 3, v213
	v_and_b32_e32 v213, 1, v213
	v_mul_u32_u24_e32 v213, 24, v213
	v_add3_u32 v212, v212, v213, v209
	v_bfe_u32 v213, v168, 6, 1
	s_cmp_lt_u32 s83, 16
	s_cbranch_scc1 .Lep1b_B
	s_sub_u32 s87, s83, 16
	s_lshr_b32 s88, s87, 3
	s_and_b32 s87, s87, 7
	s_lshl_b32 s89, s88, 3
	s_add_u32 s89, s89, 0xe0
	s_load_dwordx2 s[84:85], s[0:1], s89
	s_cmp_eq_u32 s88, 1
	s_cselect_b32 s88, 1, 0
	s_cmp_lt_u32 s87, 4
	s_cselect_b32 s88, s88, 0
	s_mov_b32 s86, 1.0
	s_cmp_eq_u32 s88, 1
	s_cselect_b32 s86, 0x3db504f3, s86
	s_lshl_b32 s87, s87, 8
	v_lshl_add_u32 v208, v213, 7, v212
	v_add_u32_e32 v208, s87, v208
	v_add_u32_e32 v209, 0x8000, v208
	v_add_u32_e32 v210, 0x10000, v208
	v_add_u32_e32 v211, 0x18000, v208
	s_waitcnt lgkmcnt(0)
	v_mul_f32_e32 v184, s86, v116
	v_mul_f32_e32 v185, s86, v117
	v_mul_f32_e32 v186, s86, v118
	v_mul_f32_e32 v187, s86, v119
	v_mul_f32_e32 v188, s86, v120
	v_mul_f32_e32 v189, s86, v121
	v_mul_f32_e32 v190, s86, v122
	v_mul_f32_e32 v191, s86, v123
	v_and_b32_sdwa v192, v184, v110 dst_sel:DWORD dst_unused:UNUSED_PAD src0_sel:WORD_1 src1_sel:DWORD
	v_and_b32_sdwa v193, v185, v110 dst_sel:DWORD dst_unused:UNUSED_PAD src0_sel:WORD_1 src1_sel:DWORD
	v_and_b32_sdwa v194, v186, v110 dst_sel:DWORD dst_unused:UNUSED_PAD src0_sel:WORD_1 src1_sel:DWORD
	v_and_b32_sdwa v195, v187, v110 dst_sel:DWORD dst_unused:UNUSED_PAD src0_sel:WORD_1 src1_sel:DWORD
	v_and_b32_sdwa v196, v188, v110 dst_sel:DWORD dst_unused:UNUSED_PAD src0_sel:WORD_1 src1_sel:DWORD
	v_and_b32_sdwa v197, v189, v110 dst_sel:DWORD dst_unused:UNUSED_PAD src0_sel:WORD_1 src1_sel:DWORD
	v_and_b32_sdwa v198, v190, v110 dst_sel:DWORD dst_unused:UNUSED_PAD src0_sel:WORD_1 src1_sel:DWORD
	v_and_b32_sdwa v199, v191, v110 dst_sel:DWORD dst_unused:UNUSED_PAD src0_sel:WORD_1 src1_sel:DWORD
	v_add3_u32 v184, v184, v192, s69
	v_add3_u32 v185, v185, v193, s69
	v_add3_u32 v186, v186, v194, s69
	v_add3_u32 v187, v187, v195, s69
	v_add3_u32 v188, v188, v196, s69
	v_add3_u32 v189, v189, v197, s69
	v_add3_u32 v190, v190, v198, s69
	v_add3_u32 v191, v191, v199, s69
	v_and_b32_e32 v185, 0xffff0000, v185
	v_and_b32_e32 v187, 0xffff0000, v187
	v_and_b32_e32 v189, 0xffff0000, v189
	v_and_b32_e32 v191, 0xffff0000, v191
	v_or_b32_sdwa v200, v185, v184 dst_sel:DWORD dst_unused:UNUSED_PAD src0_sel:DWORD src1_sel:WORD_1
	v_or_b32_sdwa v201, v187, v186 dst_sel:DWORD dst_unused:UNUSED_PAD src0_sel:DWORD src1_sel:WORD_1
	v_or_b32_sdwa v202, v189, v188 dst_sel:DWORD dst_unused:UNUSED_PAD src0_sel:DWORD src1_sel:WORD_1
	v_or_b32_sdwa v203, v191, v190 dst_sel:DWORD dst_unused:UNUSED_PAD src0_sel:DWORD src1_sel:WORD_1
	s_nop 1
	v_permlane16_swap_b32_e32 v200, v202
	v_permlane16_swap_b32_e32 v201, v203
	global_store_dwordx4 v208, v[200:203], s[84:85]
	v_mul_f32_e32 v184, s86, v124
	v_mul_f32_e32 v185, s86, v125
	v_mul_f32_e32 v186, s86, v126
	v_mul_f32_e32 v187, s86, v127
	v_mul_f32_e32 v188, s86, v128
	v_mul_f32_e32 v189, s86, v129
	v_mul_f32_e32 v190, s86, v130
	v_mul_f32_e32 v191, s86, v131
	v_and_b32_sdwa v192, v184, v110 dst_sel:DWORD dst_unused:UNUSED_PAD src0_sel:WORD_1 src1_sel:DWORD
	v_and_b32_sdwa v193, v185, v110 dst_sel:DWORD dst_unused:UNUSED_PAD src0_sel:WORD_1 src1_sel:DWORD
	v_and_b32_sdwa v194, v186, v110 dst_sel:DWORD dst_unused:UNUSED_PAD src0_sel:WORD_1 src1_sel:DWORD
	v_and_b32_sdwa v195, v187, v110 dst_sel:DWORD dst_unused:UNUSED_PAD src0_sel:WORD_1 src1_sel:DWORD
	v_and_b32_sdwa v196, v188, v110 dst_sel:DWORD dst_unused:UNUSED_PAD src0_sel:WORD_1 src1_sel:DWORD
	v_and_b32_sdwa v197, v189, v110 dst_sel:DWORD dst_unused:UNUSED_PAD src0_sel:WORD_1 src1_sel:DWORD
	v_and_b32_sdwa v198, v190, v110 dst_sel:DWORD dst_unused:UNUSED_PAD src0_sel:WORD_1 src1_sel:DWORD
	v_and_b32_sdwa v199, v191, v110 dst_sel:DWORD dst_unused:UNUSED_PAD src0_sel:WORD_1 src1_sel:DWORD
	v_add3_u32 v184, v184, v192, s69
	v_add3_u32 v185, v185, v193, s69
	v_add3_u32 v186, v186, v194, s69
	v_add3_u32 v187, v187, v195, s69
	v_add3_u32 v188, v188, v196, s69
	v_add3_u32 v189, v189, v197, s69
	v_add3_u32 v190, v190, v198, s69
	v_add3_u32 v191, v191, v199, s69
	v_and_b32_e32 v185, 0xffff0000, v185
	v_and_b32_e32 v187, 0xffff0000, v187
	v_and_b32_e32 v189, 0xffff0000, v189
	v_and_b32_e32 v191, 0xffff0000, v191
	v_or_b32_sdwa v204, v185, v184 dst_sel:DWORD dst_unused:UNUSED_PAD src0_sel:DWORD src1_sel:WORD_1
	v_or_b32_sdwa v205, v187, v186 dst_sel:DWORD dst_unused:UNUSED_PAD src0_sel:DWORD src1_sel:WORD_1
	v_or_b32_sdwa v206, v189, v188 dst_sel:DWORD dst_unused:UNUSED_PAD src0_sel:DWORD src1_sel:WORD_1
	v_or_b32_sdwa v207, v191, v190 dst_sel:DWORD dst_unused:UNUSED_PAD src0_sel:DWORD src1_sel:WORD_1
	s_nop 1
	v_permlane16_swap_b32_e32 v204, v206
	v_permlane16_swap_b32_e32 v205, v207
	global_store_dwordx4 v208, v[204:207], s[84:85] offset:64
	v_mul_f32_e32 v184, s86, v132
	v_mul_f32_e32 v185, s86, v133
	v_mul_f32_e32 v186, s86, v134
	v_mul_f32_e32 v187, s86, v135
	v_mul_f32_e32 v188, s86, v136
	v_mul_f32_e32 v189, s86, v137
	v_mul_f32_e32 v190, s86, v138
	v_mul_f32_e32 v191, s86, v139
	v_and_b32_sdwa v192, v184, v110 dst_sel:DWORD dst_unused:UNUSED_PAD src0_sel:WORD_1 src1_sel:DWORD
	v_and_b32_sdwa v193, v185, v110 dst_sel:DWORD dst_unused:UNUSED_PAD src0_sel:WORD_1 src1_sel:DWORD
	v_and_b32_sdwa v194, v186, v110 dst_sel:DWORD dst_unused:UNUSED_PAD src0_sel:WORD_1 src1_sel:DWORD
	v_and_b32_sdwa v195, v187, v110 dst_sel:DWORD dst_unused:UNUSED_PAD src0_sel:WORD_1 src1_sel:DWORD
	v_and_b32_sdwa v196, v188, v110 dst_sel:DWORD dst_unused:UNUSED_PAD src0_sel:WORD_1 src1_sel:DWORD
	v_and_b32_sdwa v197, v189, v110 dst_sel:DWORD dst_unused:UNUSED_PAD src0_sel:WORD_1 src1_sel:DWORD
	v_and_b32_sdwa v198, v190, v110 dst_sel:DWORD dst_unused:UNUSED_PAD src0_sel:WORD_1 src1_sel:DWORD
	v_and_b32_sdwa v199, v191, v110 dst_sel:DWORD dst_unused:UNUSED_PAD src0_sel:WORD_1 src1_sel:DWORD
	v_add3_u32 v184, v184, v192, s69
	v_add3_u32 v185, v185, v193, s69
	v_add3_u32 v186, v186, v194, s69
	v_add3_u32 v187, v187, v195, s69
	v_add3_u32 v188, v188, v196, s69
	v_add3_u32 v189, v189, v197, s69
	v_add3_u32 v190, v190, v198, s69
	v_add3_u32 v191, v191, v199, s69
	v_and_b32_e32 v185, 0xffff0000, v185
	v_and_b32_e32 v187, 0xffff0000, v187
	v_and_b32_e32 v189, 0xffff0000, v189
	v_and_b32_e32 v191, 0xffff0000, v191
	v_or_b32_sdwa v200, v185, v184 dst_sel:DWORD dst_unused:UNUSED_PAD src0_sel:DWORD src1_sel:WORD_1
	v_or_b32_sdwa v201, v187, v186 dst_sel:DWORD dst_unused:UNUSED_PAD src0_sel:DWORD src1_sel:WORD_1
	v_or_b32_sdwa v202, v189, v188 dst_sel:DWORD dst_unused:UNUSED_PAD src0_sel:DWORD src1_sel:WORD_1
	v_or_b32_sdwa v203, v191, v190 dst_sel:DWORD dst_unused:UNUSED_PAD src0_sel:DWORD src1_sel:WORD_1
	s_nop 1
	v_permlane16_swap_b32_e32 v200, v202
	v_permlane16_swap_b32_e32 v201, v203
	global_store_dwordx4 v209, v[200:203], s[84:85]
	v_mul_f32_e32 v184, s86, v140
	v_mul_f32_e32 v185, s86, v141
	v_mul_f32_e32 v186, s86, v142
	v_mul_f32_e32 v187, s86, v143
	v_mul_f32_e32 v188, s86, v144
	v_mul_f32_e32 v189, s86, v145
	v_mul_f32_e32 v190, s86, v146
	v_mul_f32_e32 v191, s86, v147
	v_and_b32_sdwa v192, v184, v110 dst_sel:DWORD dst_unused:UNUSED_PAD src0_sel:WORD_1 src1_sel:DWORD
	v_and_b32_sdwa v193, v185, v110 dst_sel:DWORD dst_unused:UNUSED_PAD src0_sel:WORD_1 src1_sel:DWORD
	v_and_b32_sdwa v194, v186, v110 dst_sel:DWORD dst_unused:UNUSED_PAD src0_sel:WORD_1 src1_sel:DWORD
	v_and_b32_sdwa v195, v187, v110 dst_sel:DWORD dst_unused:UNUSED_PAD src0_sel:WORD_1 src1_sel:DWORD
	v_and_b32_sdwa v196, v188, v110 dst_sel:DWORD dst_unused:UNUSED_PAD src0_sel:WORD_1 src1_sel:DWORD
	v_and_b32_sdwa v197, v189, v110 dst_sel:DWORD dst_unused:UNUSED_PAD src0_sel:WORD_1 src1_sel:DWORD
	v_and_b32_sdwa v198, v190, v110 dst_sel:DWORD dst_unused:UNUSED_PAD src0_sel:WORD_1 src1_sel:DWORD
	v_and_b32_sdwa v199, v191, v110 dst_sel:DWORD dst_unused:UNUSED_PAD src0_sel:WORD_1 src1_sel:DWORD
	v_add3_u32 v184, v184, v192, s69
	v_add3_u32 v185, v185, v193, s69
	v_add3_u32 v186, v186, v194, s69
	v_add3_u32 v187, v187, v195, s69
	v_add3_u32 v188, v188, v196, s69
	v_add3_u32 v189, v189, v197, s69
	v_add3_u32 v190, v190, v198, s69
	v_add3_u32 v191, v191, v199, s69
	v_and_b32_e32 v185, 0xffff0000, v185
	v_and_b32_e32 v187, 0xffff0000, v187
	v_and_b32_e32 v189, 0xffff0000, v189
	v_and_b32_e32 v191, 0xffff0000, v191
	v_or_b32_sdwa v204, v185, v184 dst_sel:DWORD dst_unused:UNUSED_PAD src0_sel:DWORD src1_sel:WORD_1
	v_or_b32_sdwa v205, v187, v186 dst_sel:DWORD dst_unused:UNUSED_PAD src0_sel:DWORD src1_sel:WORD_1
	v_or_b32_sdwa v206, v189, v188 dst_sel:DWORD dst_unused:UNUSED_PAD src0_sel:DWORD src1_sel:WORD_1
	v_or_b32_sdwa v207, v191, v190 dst_sel:DWORD dst_unused:UNUSED_PAD src0_sel:DWORD src1_sel:WORD_1
	s_nop 1
	v_permlane16_swap_b32_e32 v204, v206
	v_permlane16_swap_b32_e32 v205, v207
	global_store_dwordx4 v209, v[204:207], s[84:85] offset:64
	v_mul_f32_e32 v184, s86, v148
	v_mul_f32_e32 v185, s86, v149
	v_mul_f32_e32 v186, s86, v150
	v_mul_f32_e32 v187, s86, v151
	v_mul_f32_e32 v188, s86, v152
	v_mul_f32_e32 v189, s86, v153
	v_mul_f32_e32 v190, s86, v154
	v_mul_f32_e32 v191, s86, v155
	v_and_b32_sdwa v192, v184, v110 dst_sel:DWORD dst_unused:UNUSED_PAD src0_sel:WORD_1 src1_sel:DWORD
	v_and_b32_sdwa v193, v185, v110 dst_sel:DWORD dst_unused:UNUSED_PAD src0_sel:WORD_1 src1_sel:DWORD
	v_and_b32_sdwa v194, v186, v110 dst_sel:DWORD dst_unused:UNUSED_PAD src0_sel:WORD_1 src1_sel:DWORD
	v_and_b32_sdwa v195, v187, v110 dst_sel:DWORD dst_unused:UNUSED_PAD src0_sel:WORD_1 src1_sel:DWORD
	v_and_b32_sdwa v196, v188, v110 dst_sel:DWORD dst_unused:UNUSED_PAD src0_sel:WORD_1 src1_sel:DWORD
	v_and_b32_sdwa v197, v189, v110 dst_sel:DWORD dst_unused:UNUSED_PAD src0_sel:WORD_1 src1_sel:DWORD
	v_and_b32_sdwa v198, v190, v110 dst_sel:DWORD dst_unused:UNUSED_PAD src0_sel:WORD_1 src1_sel:DWORD
	v_and_b32_sdwa v199, v191, v110 dst_sel:DWORD dst_unused:UNUSED_PAD src0_sel:WORD_1 src1_sel:DWORD
	v_add3_u32 v184, v184, v192, s69
	v_add3_u32 v185, v185, v193, s69
	v_add3_u32 v186, v186, v194, s69
	v_add3_u32 v187, v187, v195, s69
	v_add3_u32 v188, v188, v196, s69
	v_add3_u32 v189, v189, v197, s69
	v_add3_u32 v190, v190, v198, s69
	v_add3_u32 v191, v191, v199, s69
	v_and_b32_e32 v185, 0xffff0000, v185
	v_and_b32_e32 v187, 0xffff0000, v187
	v_and_b32_e32 v189, 0xffff0000, v189
	v_and_b32_e32 v191, 0xffff0000, v191
	v_or_b32_sdwa v200, v185, v184 dst_sel:DWORD dst_unused:UNUSED_PAD src0_sel:DWORD src1_sel:WORD_1
	v_or_b32_sdwa v201, v187, v186 dst_sel:DWORD dst_unused:UNUSED_PAD src0_sel:DWORD src1_sel:WORD_1
	v_or_b32_sdwa v202, v189, v188 dst_sel:DWORD dst_unused:UNUSED_PAD src0_sel:DWORD src1_sel:WORD_1
	v_or_b32_sdwa v203, v191, v190 dst_sel:DWORD dst_unused:UNUSED_PAD src0_sel:DWORD src1_sel:WORD_1
	s_nop 1
	v_permlane16_swap_b32_e32 v200, v202
	v_permlane16_swap_b32_e32 v201, v203
	global_store_dwordx4 v210, v[200:203], s[84:85]
	v_mul_f32_e32 v184, s86, v156
	v_mul_f32_e32 v185, s86, v157
	v_mul_f32_e32 v186, s86, v158
	v_mul_f32_e32 v187, s86, v159
	v_mul_f32_e32 v188, s86, v160
	v_mul_f32_e32 v189, s86, v161
	v_mul_f32_e32 v190, s86, v162
	v_mul_f32_e32 v191, s86, v163
	v_and_b32_sdwa v192, v184, v110 dst_sel:DWORD dst_unused:UNUSED_PAD src0_sel:WORD_1 src1_sel:DWORD
	v_and_b32_sdwa v193, v185, v110 dst_sel:DWORD dst_unused:UNUSED_PAD src0_sel:WORD_1 src1_sel:DWORD
	v_and_b32_sdwa v194, v186, v110 dst_sel:DWORD dst_unused:UNUSED_PAD src0_sel:WORD_1 src1_sel:DWORD
	v_and_b32_sdwa v195, v187, v110 dst_sel:DWORD dst_unused:UNUSED_PAD src0_sel:WORD_1 src1_sel:DWORD
	v_and_b32_sdwa v196, v188, v110 dst_sel:DWORD dst_unused:UNUSED_PAD src0_sel:WORD_1 src1_sel:DWORD
	v_and_b32_sdwa v197, v189, v110 dst_sel:DWORD dst_unused:UNUSED_PAD src0_sel:WORD_1 src1_sel:DWORD
	v_and_b32_sdwa v198, v190, v110 dst_sel:DWORD dst_unused:UNUSED_PAD src0_sel:WORD_1 src1_sel:DWORD
	v_and_b32_sdwa v199, v191, v110 dst_sel:DWORD dst_unused:UNUSED_PAD src0_sel:WORD_1 src1_sel:DWORD
	v_add3_u32 v184, v184, v192, s69
	v_add3_u32 v185, v185, v193, s69
	v_add3_u32 v186, v186, v194, s69
	v_add3_u32 v187, v187, v195, s69
	v_add3_u32 v188, v188, v196, s69
	v_add3_u32 v189, v189, v197, s69
	v_add3_u32 v190, v190, v198, s69
	v_add3_u32 v191, v191, v199, s69
	v_and_b32_e32 v185, 0xffff0000, v185
	v_and_b32_e32 v187, 0xffff0000, v187
	v_and_b32_e32 v189, 0xffff0000, v189
	v_and_b32_e32 v191, 0xffff0000, v191
	v_or_b32_sdwa v204, v185, v184 dst_sel:DWORD dst_unused:UNUSED_PAD src0_sel:DWORD src1_sel:WORD_1
	v_or_b32_sdwa v205, v187, v186 dst_sel:DWORD dst_unused:UNUSED_PAD src0_sel:DWORD src1_sel:WORD_1
	v_or_b32_sdwa v206, v189, v188 dst_sel:DWORD dst_unused:UNUSED_PAD src0_sel:DWORD src1_sel:WORD_1
	v_or_b32_sdwa v207, v191, v190 dst_sel:DWORD dst_unused:UNUSED_PAD src0_sel:DWORD src1_sel:WORD_1
	s_nop 1
	v_permlane16_swap_b32_e32 v204, v206
	v_permlane16_swap_b32_e32 v205, v207
	global_store_dwordx4 v210, v[204:207], s[84:85] offset:64
	v_mul_f32_e32 v184, s86, v164
	v_mul_f32_e32 v185, s86, v165
	v_mul_f32_e32 v186, s86, v166
	v_mul_f32_e32 v187, s86, v167
	v_mul_f32_e32 v188, s86, v172
	v_mul_f32_e32 v189, s86, v173
	v_mul_f32_e32 v190, s86, v174
	v_mul_f32_e32 v191, s86, v175
	v_and_b32_sdwa v192, v184, v110 dst_sel:DWORD dst_unused:UNUSED_PAD src0_sel:WORD_1 src1_sel:DWORD
	v_and_b32_sdwa v193, v185, v110 dst_sel:DWORD dst_unused:UNUSED_PAD src0_sel:WORD_1 src1_sel:DWORD
	v_and_b32_sdwa v194, v186, v110 dst_sel:DWORD dst_unused:UNUSED_PAD src0_sel:WORD_1 src1_sel:DWORD
	v_and_b32_sdwa v195, v187, v110 dst_sel:DWORD dst_unused:UNUSED_PAD src0_sel:WORD_1 src1_sel:DWORD
	v_and_b32_sdwa v196, v188, v110 dst_sel:DWORD dst_unused:UNUSED_PAD src0_sel:WORD_1 src1_sel:DWORD
	v_and_b32_sdwa v197, v189, v110 dst_sel:DWORD dst_unused:UNUSED_PAD src0_sel:WORD_1 src1_sel:DWORD
	v_and_b32_sdwa v198, v190, v110 dst_sel:DWORD dst_unused:UNUSED_PAD src0_sel:WORD_1 src1_sel:DWORD
	v_and_b32_sdwa v199, v191, v110 dst_sel:DWORD dst_unused:UNUSED_PAD src0_sel:WORD_1 src1_sel:DWORD
	v_add3_u32 v184, v184, v192, s69
	v_add3_u32 v185, v185, v193, s69
	v_add3_u32 v186, v186, v194, s69
	v_add3_u32 v187, v187, v195, s69
	v_add3_u32 v188, v188, v196, s69
	v_add3_u32 v189, v189, v197, s69
	v_add3_u32 v190, v190, v198, s69
	v_add3_u32 v191, v191, v199, s69
	v_and_b32_e32 v185, 0xffff0000, v185
	v_and_b32_e32 v187, 0xffff0000, v187
	v_and_b32_e32 v189, 0xffff0000, v189
	v_and_b32_e32 v191, 0xffff0000, v191
	v_or_b32_sdwa v200, v185, v184 dst_sel:DWORD dst_unused:UNUSED_PAD src0_sel:DWORD src1_sel:WORD_1
	v_or_b32_sdwa v201, v187, v186 dst_sel:DWORD dst_unused:UNUSED_PAD src0_sel:DWORD src1_sel:WORD_1
	v_or_b32_sdwa v202, v189, v188 dst_sel:DWORD dst_unused:UNUSED_PAD src0_sel:DWORD src1_sel:WORD_1
	v_or_b32_sdwa v203, v191, v190 dst_sel:DWORD dst_unused:UNUSED_PAD src0_sel:DWORD src1_sel:WORD_1
	s_nop 1
	v_permlane16_swap_b32_e32 v200, v202
	v_permlane16_swap_b32_e32 v201, v203
	global_store_dwordx4 v211, v[200:203], s[84:85]
	v_mul_f32_e32 v184, s86, v176
	v_mul_f32_e32 v185, s86, v177
	v_mul_f32_e32 v186, s86, v178
	v_mul_f32_e32 v187, s86, v179
	v_mul_f32_e32 v188, s86, v180
	v_mul_f32_e32 v189, s86, v181
	v_mul_f32_e32 v190, s86, v182
	v_mul_f32_e32 v191, s86, v183
	v_and_b32_sdwa v192, v184, v110 dst_sel:DWORD dst_unused:UNUSED_PAD src0_sel:WORD_1 src1_sel:DWORD
	v_and_b32_sdwa v193, v185, v110 dst_sel:DWORD dst_unused:UNUSED_PAD src0_sel:WORD_1 src1_sel:DWORD
	v_and_b32_sdwa v194, v186, v110 dst_sel:DWORD dst_unused:UNUSED_PAD src0_sel:WORD_1 src1_sel:DWORD
	v_and_b32_sdwa v195, v187, v110 dst_sel:DWORD dst_unused:UNUSED_PAD src0_sel:WORD_1 src1_sel:DWORD
	v_and_b32_sdwa v196, v188, v110 dst_sel:DWORD dst_unused:UNUSED_PAD src0_sel:WORD_1 src1_sel:DWORD
	v_and_b32_sdwa v197, v189, v110 dst_sel:DWORD dst_unused:UNUSED_PAD src0_sel:WORD_1 src1_sel:DWORD
	v_and_b32_sdwa v198, v190, v110 dst_sel:DWORD dst_unused:UNUSED_PAD src0_sel:WORD_1 src1_sel:DWORD
	v_and_b32_sdwa v199, v191, v110 dst_sel:DWORD dst_unused:UNUSED_PAD src0_sel:WORD_1 src1_sel:DWORD
	v_add3_u32 v184, v184, v192, s69
	v_add3_u32 v185, v185, v193, s69
	v_add3_u32 v186, v186, v194, s69
	v_add3_u32 v187, v187, v195, s69
	v_add3_u32 v188, v188, v196, s69
	v_add3_u32 v189, v189, v197, s69
	v_add3_u32 v190, v190, v198, s69
	v_add3_u32 v191, v191, v199, s69
	v_and_b32_e32 v185, 0xffff0000, v185
	v_and_b32_e32 v187, 0xffff0000, v187
	v_and_b32_e32 v189, 0xffff0000, v189
	v_and_b32_e32 v191, 0xffff0000, v191
	v_or_b32_sdwa v204, v185, v184 dst_sel:DWORD dst_unused:UNUSED_PAD src0_sel:DWORD src1_sel:WORD_1
	v_or_b32_sdwa v205, v187, v186 dst_sel:DWORD dst_unused:UNUSED_PAD src0_sel:DWORD src1_sel:WORD_1
	v_or_b32_sdwa v206, v189, v188 dst_sel:DWORD dst_unused:UNUSED_PAD src0_sel:DWORD src1_sel:WORD_1
	v_or_b32_sdwa v207, v191, v190 dst_sel:DWORD dst_unused:UNUSED_PAD src0_sel:DWORD src1_sel:WORD_1
	s_nop 1
	v_permlane16_swap_b32_e32 v204, v206
	v_permlane16_swap_b32_e32 v205, v207
	global_store_dwordx4 v211, v[204:207], s[84:85] offset:64
	s_branch .Lep1b_done
.Lep1b_B:
	s_load_dwordx2 s[84:85], s[0:1], 0xd8
	s_lshl_b32 s87, s83, 7
	v_lshl_add_u32 v208, v213, 6, v212
	v_add_u32_e32 v208, s87, v208
	v_add_u32_e32 v209, 0x8000, v208
	v_add_u32_e32 v210, 0x10000, v208
	v_add_u32_e32 v211, 0x18000, v208
	s_waitcnt lgkmcnt(0)
	v_mul_f32_e32 v184, v124, v116
	v_mul_f32_e32 v185, v125, v117
	v_mul_f32_e32 v186, v126, v118
	v_mul_f32_e32 v187, v127, v119
	v_mul_f32_e32 v188, v128, v120
	v_mul_f32_e32 v189, v129, v121
	v_mul_f32_e32 v190, v130, v122
	v_mul_f32_e32 v191, v131, v123
	v_and_b32_sdwa v192, v184, v110 dst_sel:DWORD dst_unused:UNUSED_PAD src0_sel:WORD_1 src1_sel:DWORD
	v_and_b32_sdwa v193, v185, v110 dst_sel:DWORD dst_unused:UNUSED_PAD src0_sel:WORD_1 src1_sel:DWORD
	v_and_b32_sdwa v194, v186, v110 dst_sel:DWORD dst_unused:UNUSED_PAD src0_sel:WORD_1 src1_sel:DWORD
	v_and_b32_sdwa v195, v187, v110 dst_sel:DWORD dst_unused:UNUSED_PAD src0_sel:WORD_1 src1_sel:DWORD
	v_and_b32_sdwa v196, v188, v110 dst_sel:DWORD dst_unused:UNUSED_PAD src0_sel:WORD_1 src1_sel:DWORD
	v_and_b32_sdwa v197, v189, v110 dst_sel:DWORD dst_unused:UNUSED_PAD src0_sel:WORD_1 src1_sel:DWORD
	v_and_b32_sdwa v198, v190, v110 dst_sel:DWORD dst_unused:UNUSED_PAD src0_sel:WORD_1 src1_sel:DWORD
	v_and_b32_sdwa v199, v191, v110 dst_sel:DWORD dst_unused:UNUSED_PAD src0_sel:WORD_1 src1_sel:DWORD
	v_add3_u32 v184, v184, v192, s69
	v_add3_u32 v185, v185, v193, s69
	v_add3_u32 v186, v186, v194, s69
	v_add3_u32 v187, v187, v195, s69
	v_add3_u32 v188, v188, v196, s69
	v_add3_u32 v189, v189, v197, s69
	v_add3_u32 v190, v190, v198, s69
	v_add3_u32 v191, v191, v199, s69
	v_and_b32_e32 v185, 0xffff0000, v185
	v_and_b32_e32 v187, 0xffff0000, v187
	v_and_b32_e32 v189, 0xffff0000, v189
	v_and_b32_e32 v191, 0xffff0000, v191
	v_or_b32_sdwa v200, v185, v184 dst_sel:DWORD dst_unused:UNUSED_PAD src0_sel:DWORD src1_sel:WORD_1
	v_or_b32_sdwa v201, v187, v186 dst_sel:DWORD dst_unused:UNUSED_PAD src0_sel:DWORD src1_sel:WORD_1
	v_or_b32_sdwa v202, v189, v188 dst_sel:DWORD dst_unused:UNUSED_PAD src0_sel:DWORD src1_sel:WORD_1
	v_or_b32_sdwa v203, v191, v190 dst_sel:DWORD dst_unused:UNUSED_PAD src0_sel:DWORD src1_sel:WORD_1
	s_nop 1
	v_permlane16_swap_b32_e32 v200, v202
	v_permlane16_swap_b32_e32 v201, v203
	global_store_dwordx4 v208, v[200:203], s[84:85]
	v_mul_f32_e32 v184, v140, v132
	v_mul_f32_e32 v185, v141, v133
	v_mul_f32_e32 v186, v142, v134
	v_mul_f32_e32 v187, v143, v135
	v_mul_f32_e32 v188, v144, v136
	v_mul_f32_e32 v189, v145, v137
	v_mul_f32_e32 v190, v146, v138
	v_mul_f32_e32 v191, v147, v139
	v_and_b32_sdwa v192, v184, v110 dst_sel:DWORD dst_unused:UNUSED_PAD src0_sel:WORD_1 src1_sel:DWORD
	v_and_b32_sdwa v193, v185, v110 dst_sel:DWORD dst_unused:UNUSED_PAD src0_sel:WORD_1 src1_sel:DWORD
	v_and_b32_sdwa v194, v186, v110 dst_sel:DWORD dst_unused:UNUSED_PAD src0_sel:WORD_1 src1_sel:DWORD
	v_and_b32_sdwa v195, v187, v110 dst_sel:DWORD dst_unused:UNUSED_PAD src0_sel:WORD_1 src1_sel:DWORD
	v_and_b32_sdwa v196, v188, v110 dst_sel:DWORD dst_unused:UNUSED_PAD src0_sel:WORD_1 src1_sel:DWORD
	v_and_b32_sdwa v197, v189, v110 dst_sel:DWORD dst_unused:UNUSED_PAD src0_sel:WORD_1 src1_sel:DWORD
	v_and_b32_sdwa v198, v190, v110 dst_sel:DWORD dst_unused:UNUSED_PAD src0_sel:WORD_1 src1_sel:DWORD
	v_and_b32_sdwa v199, v191, v110 dst_sel:DWORD dst_unused:UNUSED_PAD src0_sel:WORD_1 src1_sel:DWORD
	v_add3_u32 v184, v184, v192, s69
	v_add3_u32 v185, v185, v193, s69
	v_add3_u32 v186, v186, v194, s69
	v_add3_u32 v187, v187, v195, s69
	v_add3_u32 v188, v188, v196, s69
	v_add3_u32 v189, v189, v197, s69
	v_add3_u32 v190, v190, v198, s69
	v_add3_u32 v191, v191, v199, s69
	v_and_b32_e32 v185, 0xffff0000, v185
	v_and_b32_e32 v187, 0xffff0000, v187
	v_and_b32_e32 v189, 0xffff0000, v189
	v_and_b32_e32 v191, 0xffff0000, v191
	v_or_b32_sdwa v204, v185, v184 dst_sel:DWORD dst_unused:UNUSED_PAD src0_sel:DWORD src1_sel:WORD_1
	v_or_b32_sdwa v205, v187, v186 dst_sel:DWORD dst_unused:UNUSED_PAD src0_sel:DWORD src1_sel:WORD_1
	v_or_b32_sdwa v206, v189, v188 dst_sel:DWORD dst_unused:UNUSED_PAD src0_sel:DWORD src1_sel:WORD_1
	v_or_b32_sdwa v207, v191, v190 dst_sel:DWORD dst_unused:UNUSED_PAD src0_sel:DWORD src1_sel:WORD_1
	s_nop 1
	v_permlane16_swap_b32_e32 v204, v206
	v_permlane16_swap_b32_e32 v205, v207
	global_store_dwordx4 v209, v[204:207], s[84:85]
	v_mul_f32_e32 v184, v156, v148
	v_mul_f32_e32 v185, v157, v149
	v_mul_f32_e32 v186, v158, v150
	v_mul_f32_e32 v187, v159, v151
	v_mul_f32_e32 v188, v160, v152
	v_mul_f32_e32 v189, v161, v153
	v_mul_f32_e32 v190, v162, v154
	v_mul_f32_e32 v191, v163, v155
	v_and_b32_sdwa v192, v184, v110 dst_sel:DWORD dst_unused:UNUSED_PAD src0_sel:WORD_1 src1_sel:DWORD
	v_and_b32_sdwa v193, v185, v110 dst_sel:DWORD dst_unused:UNUSED_PAD src0_sel:WORD_1 src1_sel:DWORD
	v_and_b32_sdwa v194, v186, v110 dst_sel:DWORD dst_unused:UNUSED_PAD src0_sel:WORD_1 src1_sel:DWORD
	v_and_b32_sdwa v195, v187, v110 dst_sel:DWORD dst_unused:UNUSED_PAD src0_sel:WORD_1 src1_sel:DWORD
	v_and_b32_sdwa v196, v188, v110 dst_sel:DWORD dst_unused:UNUSED_PAD src0_sel:WORD_1 src1_sel:DWORD
	v_and_b32_sdwa v197, v189, v110 dst_sel:DWORD dst_unused:UNUSED_PAD src0_sel:WORD_1 src1_sel:DWORD
	v_and_b32_sdwa v198, v190, v110 dst_sel:DWORD dst_unused:UNUSED_PAD src0_sel:WORD_1 src1_sel:DWORD
	v_and_b32_sdwa v199, v191, v110 dst_sel:DWORD dst_unused:UNUSED_PAD src0_sel:WORD_1 src1_sel:DWORD
	v_add3_u32 v184, v184, v192, s69
	v_add3_u32 v185, v185, v193, s69
	v_add3_u32 v186, v186, v194, s69
	v_add3_u32 v187, v187, v195, s69
	v_add3_u32 v188, v188, v196, s69
	v_add3_u32 v189, v189, v197, s69
	v_add3_u32 v190, v190, v198, s69
	v_add3_u32 v191, v191, v199, s69
	v_and_b32_e32 v185, 0xffff0000, v185
	v_and_b32_e32 v187, 0xffff0000, v187
	v_and_b32_e32 v189, 0xffff0000, v189
	v_and_b32_e32 v191, 0xffff0000, v191
	v_or_b32_sdwa v200, v185, v184 dst_sel:DWORD dst_unused:UNUSED_PAD src0_sel:DWORD src1_sel:WORD_1
	v_or_b32_sdwa v201, v187, v186 dst_sel:DWORD dst_unused:UNUSED_PAD src0_sel:DWORD src1_sel:WORD_1
	v_or_b32_sdwa v202, v189, v188 dst_sel:DWORD dst_unused:UNUSED_PAD src0_sel:DWORD src1_sel:WORD_1
	v_or_b32_sdwa v203, v191, v190 dst_sel:DWORD dst_unused:UNUSED_PAD src0_sel:DWORD src1_sel:WORD_1
	s_nop 1
	v_permlane16_swap_b32_e32 v200, v202
	v_permlane16_swap_b32_e32 v201, v203
	global_store_dwordx4 v210, v[200:203], s[84:85]
	v_mul_f32_e32 v184, v176, v164
	v_mul_f32_e32 v185, v177, v165
	v_mul_f32_e32 v186, v178, v166
	v_mul_f32_e32 v187, v179, v167
	v_mul_f32_e32 v188, v180, v172
	v_mul_f32_e32 v189, v181, v173
	v_mul_f32_e32 v190, v182, v174
	v_mul_f32_e32 v191, v183, v175
	v_and_b32_sdwa v192, v184, v110 dst_sel:DWORD dst_unused:UNUSED_PAD src0_sel:WORD_1 src1_sel:DWORD
	v_and_b32_sdwa v193, v185, v110 dst_sel:DWORD dst_unused:UNUSED_PAD src0_sel:WORD_1 src1_sel:DWORD
	v_and_b32_sdwa v194, v186, v110 dst_sel:DWORD dst_unused:UNUSED_PAD src0_sel:WORD_1 src1_sel:DWORD
	v_and_b32_sdwa v195, v187, v110 dst_sel:DWORD dst_unused:UNUSED_PAD src0_sel:WORD_1 src1_sel:DWORD
	v_and_b32_sdwa v196, v188, v110 dst_sel:DWORD dst_unused:UNUSED_PAD src0_sel:WORD_1 src1_sel:DWORD
	v_and_b32_sdwa v197, v189, v110 dst_sel:DWORD dst_unused:UNUSED_PAD src0_sel:WORD_1 src1_sel:DWORD
	v_and_b32_sdwa v198, v190, v110 dst_sel:DWORD dst_unused:UNUSED_PAD src0_sel:WORD_1 src1_sel:DWORD
	v_and_b32_sdwa v199, v191, v110 dst_sel:DWORD dst_unused:UNUSED_PAD src0_sel:WORD_1 src1_sel:DWORD
	v_add3_u32 v184, v184, v192, s69
	v_add3_u32 v185, v185, v193, s69
	v_add3_u32 v186, v186, v194, s69
	v_add3_u32 v187, v187, v195, s69
	v_add3_u32 v188, v188, v196, s69
	v_add3_u32 v189, v189, v197, s69
	v_add3_u32 v190, v190, v198, s69
	v_add3_u32 v191, v191, v199, s69
	v_and_b32_e32 v185, 0xffff0000, v185
	v_and_b32_e32 v187, 0xffff0000, v187
	v_and_b32_e32 v189, 0xffff0000, v189
	v_and_b32_e32 v191, 0xffff0000, v191
	v_or_b32_sdwa v204, v185, v184 dst_sel:DWORD dst_unused:UNUSED_PAD src0_sel:DWORD src1_sel:WORD_1
	v_or_b32_sdwa v205, v187, v186 dst_sel:DWORD dst_unused:UNUSED_PAD src0_sel:DWORD src1_sel:WORD_1
	v_or_b32_sdwa v206, v189, v188 dst_sel:DWORD dst_unused:UNUSED_PAD src0_sel:DWORD src1_sel:WORD_1
	v_or_b32_sdwa v207, v191, v190 dst_sel:DWORD dst_unused:UNUSED_PAD src0_sel:DWORD src1_sel:WORD_1
	s_nop 1
	v_permlane16_swap_b32_e32 v204, v206
	v_permlane16_swap_b32_e32 v205, v207
	global_store_dwordx4 v211, v[204:207], s[84:85]

.Lgp1_single:
	s_mov_b32 s95, 0
	s_branch .LBB0_99

.Lgp9_done:
	v_lshl_add_u32 v166, s50, 7, v90
	v_lshl_or_b32 v198, s48, 7, v91
	v_ashrrev_i32_e32 v199, 31, v198
	v_ashrrev_i32_e32 v167, 31, v166
	v_lshl_add_u64 v[198:199], v[198:199], 1, s[14:15]
	v_lshlrev_b64 v[200:201], 12, v[166:167]
	v_lshl_add_u64 v[200:201], v[198:199], 0, v[200:201]
	s_lshl_b32 s44, s50, 6
	s_lshl_b32 s49, s48, 2
	s_add_i32 s49, s49, s44
	s_lshl_b32 s44, s50, 18
	s_lshl_b32 s48, s48, 14
	s_add_i32 s48, s44, s48
	s_mov_b32 s50, 0
	s_waitcnt lgkmcnt(0)
	s_waitcnt lgkmcnt(0)
	s_waitcnt vmcnt(0) lgkmcnt(0)
	s_waitcnt lgkmcnt(0)
	s_waitcnt lgkmcnt(0)
	s_nop 5
	v_and_b32_sdwa v111, v62, v108 dst_sel:DWORD dst_unused:UNUSED_PAD src0_sel:WORD_1 src1_sel:DWORD
	v_add3_u32 v62, v62, v111, s66
	v_and_b32_sdwa v111, v63, v108 dst_sel:DWORD dst_unused:UNUSED_PAD src0_sel:WORD_1 src1_sel:DWORD
	v_and_b32_sdwa v145, v60, v108 dst_sel:DWORD dst_unused:UNUSED_PAD src0_sel:WORD_1 src1_sel:DWORD
	v_add3_u32 v63, v63, v111, s66
	v_add3_u32 v60, v60, v145, s66
	v_and_b32_e32 v63, 0xffff0000, v63
	v_and_b32_sdwa v112, v61, v108 dst_sel:DWORD dst_unused:UNUSED_PAD src0_sel:WORD_1 src1_sel:DWORD
	v_add3_u32 v61, v61, v112, s66
	v_and_b32_e32 v78, 0xffff0000, v61
	v_or_b32_sdwa v61, v63, v62 dst_sel:DWORD dst_unused:UNUSED_PAD src0_sel:DWORD src1_sel:WORD_1
	v_or_b32_sdwa v60, v78, v60 dst_sel:DWORD dst_unused:UNUSED_PAD src0_sel:DWORD src1_sel:WORD_1
	global_store_dwordx2 v[200:201], v[60:61], off
	s_nop 1
	v_and_b32_sdwa v60, v58, v108 dst_sel:DWORD dst_unused:UNUSED_PAD src0_sel:WORD_1 src1_sel:DWORD
	v_and_b32_sdwa v61, v56, v108 dst_sel:DWORD dst_unused:UNUSED_PAD src0_sel:WORD_1 src1_sel:DWORD
	v_add3_u32 v56, v56, v61, s66
	v_add3_u32 v58, v58, v60, s66
	v_and_b32_sdwa v60, v59, v108 dst_sel:DWORD dst_unused:UNUSED_PAD src0_sel:WORD_1 src1_sel:DWORD
	v_and_b32_sdwa v61, v57, v108 dst_sel:DWORD dst_unused:UNUSED_PAD src0_sel:WORD_1 src1_sel:DWORD
	v_add3_u32 v59, v59, v60, s66
	v_add3_u32 v57, v57, v61, s66
	v_and_b32_e32 v59, 0xffff0000, v59
	v_and_b32_e32 v60, 0xffff0000, v57
	v_or_b32_sdwa v57, v59, v58 dst_sel:DWORD dst_unused:UNUSED_PAD src0_sel:DWORD src1_sel:WORD_1
	v_or_b32_sdwa v56, v60, v56 dst_sel:DWORD dst_unused:UNUSED_PAD src0_sel:DWORD src1_sel:WORD_1
	global_store_dwordx2 v[200:201], v[56:57], off offset:32
	v_and_b32_sdwa v56, v54, v108 dst_sel:DWORD dst_unused:UNUSED_PAD src0_sel:WORD_1 src1_sel:DWORD
	v_and_b32_sdwa v57, v52, v108 dst_sel:DWORD dst_unused:UNUSED_PAD src0_sel:WORD_1 src1_sel:DWORD
	v_add3_u32 v52, v52, v57, s66
	v_add3_u32 v54, v54, v56, s66
	v_and_b32_sdwa v56, v55, v108 dst_sel:DWORD dst_unused:UNUSED_PAD src0_sel:WORD_1 src1_sel:DWORD
	v_and_b32_sdwa v57, v53, v108 dst_sel:DWORD dst_unused:UNUSED_PAD src0_sel:WORD_1 src1_sel:DWORD
	v_add3_u32 v55, v55, v56, s66
	v_add3_u32 v53, v53, v57, s66
	v_and_b32_e32 v55, 0xffff0000, v55
	v_and_b32_e32 v56, 0xffff0000, v53
	v_or_b32_sdwa v53, v55, v54 dst_sel:DWORD dst_unused:UNUSED_PAD src0_sel:DWORD src1_sel:WORD_1
	v_or_b32_sdwa v52, v56, v52 dst_sel:DWORD dst_unused:UNUSED_PAD src0_sel:DWORD src1_sel:WORD_1
	global_store_dwordx2 v[200:201], v[52:53], off offset:64
	s_nop 2
	v_and_b32_sdwa v52, v50, v108 dst_sel:DWORD dst_unused:UNUSED_PAD src0_sel:WORD_1 src1_sel:DWORD
	v_and_b32_sdwa v53, v48, v108 dst_sel:DWORD dst_unused:UNUSED_PAD src0_sel:WORD_1 src1_sel:DWORD
	v_add3_u32 v48, v48, v53, s66
	v_add3_u32 v50, v50, v52, s66
	v_and_b32_sdwa v52, v51, v108 dst_sel:DWORD dst_unused:UNUSED_PAD src0_sel:WORD_1 src1_sel:DWORD
	v_and_b32_sdwa v53, v49, v108 dst_sel:DWORD dst_unused:UNUSED_PAD src0_sel:WORD_1 src1_sel:DWORD
	v_add3_u32 v51, v51, v52, s66
	v_add3_u32 v49, v49, v53, s66
	v_and_b32_e32 v51, 0xffff0000, v51
	v_and_b32_e32 v52, 0xffff0000, v49
	v_or_b32_sdwa v49, v51, v50 dst_sel:DWORD dst_unused:UNUSED_PAD src0_sel:DWORD src1_sel:WORD_1
	v_or_b32_sdwa v48, v52, v48 dst_sel:DWORD dst_unused:UNUSED_PAD src0_sel:DWORD src1_sel:WORD_1
	v_and_b32_sdwa v50, v46, v108 dst_sel:DWORD dst_unused:UNUSED_PAD src0_sel:WORD_1 src1_sel:DWORD
	v_and_b32_sdwa v51, v44, v108 dst_sel:DWORD dst_unused:UNUSED_PAD src0_sel:WORD_1 src1_sel:DWORD
	global_store_dwordx2 v[200:201], v[48:49], off offset:96
	v_or_b32_e32 v48, 16, v166
	v_add3_u32 v44, v44, v51, s66
	v_add3_u32 v46, v46, v50, s66
	v_and_b32_sdwa v50, v47, v108 dst_sel:DWORD dst_unused:UNUSED_PAD src0_sel:WORD_1 src1_sel:DWORD
	v_and_b32_sdwa v51, v45, v108 dst_sel:DWORD dst_unused:UNUSED_PAD src0_sel:WORD_1 src1_sel:DWORD
	v_ashrrev_i32_e32 v49, 31, v48
	v_add3_u32 v47, v47, v50, s66
	v_add3_u32 v45, v45, v51, s66
	v_lshlrev_b64 v[48:49], 12, v[48:49]
	v_and_b32_e32 v47, 0xffff0000, v47
	v_and_b32_e32 v50, 0xffff0000, v45
	v_lshl_add_u64 v[48:49], v[198:199], 0, v[48:49]
	v_or_b32_sdwa v45, v47, v46 dst_sel:DWORD dst_unused:UNUSED_PAD src0_sel:DWORD src1_sel:WORD_1
	v_or_b32_sdwa v44, v50, v44 dst_sel:DWORD dst_unused:UNUSED_PAD src0_sel:DWORD src1_sel:WORD_1
	global_store_dwordx2 v[48:49], v[44:45], off
	v_and_b32_sdwa v44, v42, v108 dst_sel:DWORD dst_unused:UNUSED_PAD src0_sel:WORD_1 src1_sel:DWORD
	v_and_b32_sdwa v45, v40, v108 dst_sel:DWORD dst_unused:UNUSED_PAD src0_sel:WORD_1 src1_sel:DWORD
	v_add3_u32 v40, v40, v45, s66
	v_add3_u32 v42, v42, v44, s66
	v_and_b32_sdwa v44, v43, v108 dst_sel:DWORD dst_unused:UNUSED_PAD src0_sel:WORD_1 src1_sel:DWORD
	v_and_b32_sdwa v45, v41, v108 dst_sel:DWORD dst_unused:UNUSED_PAD src0_sel:WORD_1 src1_sel:DWORD
	v_add3_u32 v43, v43, v44, s66
	v_add3_u32 v41, v41, v45, s66
	v_and_b32_e32 v43, 0xffff0000, v43
	v_and_b32_e32 v44, 0xffff0000, v41
	v_or_b32_sdwa v41, v43, v42 dst_sel:DWORD dst_unused:UNUSED_PAD src0_sel:DWORD src1_sel:WORD_1
	v_or_b32_sdwa v40, v44, v40 dst_sel:DWORD dst_unused:UNUSED_PAD src0_sel:DWORD src1_sel:WORD_1
	global_store_dwordx2 v[48:49], v[40:41], off offset:32
	v_and_b32_sdwa v40, v38, v108 dst_sel:DWORD dst_unused:UNUSED_PAD src0_sel:WORD_1 src1_sel:DWORD
	v_and_b32_sdwa v41, v36, v108 dst_sel:DWORD dst_unused:UNUSED_PAD src0_sel:WORD_1 src1_sel:DWORD
	v_add3_u32 v36, v36, v41, s66
	v_add3_u32 v38, v38, v40, s66
	v_and_b32_sdwa v40, v39, v108 dst_sel:DWORD dst_unused:UNUSED_PAD src0_sel:WORD_1 src1_sel:DWORD
	v_and_b32_sdwa v41, v37, v108 dst_sel:DWORD dst_unused:UNUSED_PAD src0_sel:WORD_1 src1_sel:DWORD
	v_add3_u32 v39, v39, v40, s66
	v_add3_u32 v37, v37, v41, s66
	v_and_b32_e32 v39, 0xffff0000, v39
	v_and_b32_e32 v40, 0xffff0000, v37
	v_or_b32_sdwa v37, v39, v38 dst_sel:DWORD dst_unused:UNUSED_PAD src0_sel:DWORD src1_sel:WORD_1
	v_or_b32_sdwa v36, v40, v36 dst_sel:DWORD dst_unused:UNUSED_PAD src0_sel:DWORD src1_sel:WORD_1
	global_store_dwordx2 v[48:49], v[36:37], off offset:64
	v_and_b32_sdwa v36, v34, v108 dst_sel:DWORD dst_unused:UNUSED_PAD src0_sel:WORD_1 src1_sel:DWORD
	v_and_b32_sdwa v37, v32, v108 dst_sel:DWORD dst_unused:UNUSED_PAD src0_sel:WORD_1 src1_sel:DWORD
	v_add3_u32 v32, v32, v37, s66
	v_add3_u32 v34, v34, v36, s66
	v_and_b32_sdwa v36, v35, v108 dst_sel:DWORD dst_unused:UNUSED_PAD src0_sel:WORD_1 src1_sel:DWORD
	v_and_b32_sdwa v37, v33, v108 dst_sel:DWORD dst_unused:UNUSED_PAD src0_sel:WORD_1 src1_sel:DWORD
	v_add3_u32 v35, v35, v36, s66
	v_add3_u32 v33, v33, v37, s66
	v_and_b32_e32 v35, 0xffff0000, v35
	v_and_b32_e32 v36, 0xffff0000, v33
	v_or_b32_sdwa v33, v35, v34 dst_sel:DWORD dst_unused:UNUSED_PAD src0_sel:DWORD src1_sel:WORD_1
	v_or_b32_sdwa v32, v36, v32 dst_sel:DWORD dst_unused:UNUSED_PAD src0_sel:DWORD src1_sel:WORD_1
	v_and_b32_sdwa v34, v30, v108 dst_sel:DWORD dst_unused:UNUSED_PAD src0_sel:WORD_1 src1_sel:DWORD
	v_and_b32_sdwa v35, v28, v108 dst_sel:DWORD dst_unused:UNUSED_PAD src0_sel:WORD_1 src1_sel:DWORD
	global_store_dwordx2 v[48:49], v[32:33], off offset:96
	v_or_b32_e32 v32, 32, v166
	v_add3_u32 v28, v28, v35, s66
	v_add3_u32 v30, v30, v34, s66
	v_and_b32_sdwa v34, v31, v108 dst_sel:DWORD dst_unused:UNUSED_PAD src0_sel:WORD_1 src1_sel:DWORD
	v_and_b32_sdwa v35, v29, v108 dst_sel:DWORD dst_unused:UNUSED_PAD src0_sel:WORD_1 src1_sel:DWORD
	v_ashrrev_i32_e32 v33, 31, v32
	v_add3_u32 v31, v31, v34, s66
	v_add3_u32 v29, v29, v35, s66
	v_lshlrev_b64 v[32:33], 12, v[32:33]
	v_and_b32_e32 v31, 0xffff0000, v31
	v_and_b32_e32 v34, 0xffff0000, v29
	v_lshl_add_u64 v[32:33], v[198:199], 0, v[32:33]
	v_or_b32_sdwa v29, v31, v30 dst_sel:DWORD dst_unused:UNUSED_PAD src0_sel:DWORD src1_sel:WORD_1
	v_or_b32_sdwa v28, v34, v28 dst_sel:DWORD dst_unused:UNUSED_PAD src0_sel:DWORD src1_sel:WORD_1
	global_store_dwordx2 v[32:33], v[28:29], off
	v_and_b32_sdwa v28, v26, v108 dst_sel:DWORD dst_unused:UNUSED_PAD src0_sel:WORD_1 src1_sel:DWORD
	v_and_b32_sdwa v29, v24, v108 dst_sel:DWORD dst_unused:UNUSED_PAD src0_sel:WORD_1 src1_sel:DWORD
	v_add3_u32 v24, v24, v29, s66
	v_add3_u32 v26, v26, v28, s66
	v_and_b32_sdwa v28, v27, v108 dst_sel:DWORD dst_unused:UNUSED_PAD src0_sel:WORD_1 src1_sel:DWORD
	v_and_b32_sdwa v29, v25, v108 dst_sel:DWORD dst_unused:UNUSED_PAD src0_sel:WORD_1 src1_sel:DWORD
	v_add3_u32 v27, v27, v28, s66
	v_add3_u32 v25, v25, v29, s66
	v_and_b32_e32 v27, 0xffff0000, v27
	v_and_b32_e32 v28, 0xffff0000, v25
	v_or_b32_sdwa v25, v27, v26 dst_sel:DWORD dst_unused:UNUSED_PAD src0_sel:DWORD src1_sel:WORD_1
	v_or_b32_sdwa v24, v28, v24 dst_sel:DWORD dst_unused:UNUSED_PAD src0_sel:DWORD src1_sel:WORD_1
	global_store_dwordx2 v[32:33], v[24:25], off offset:32
	v_and_b32_sdwa v24, v22, v108 dst_sel:DWORD dst_unused:UNUSED_PAD src0_sel:WORD_1 src1_sel:DWORD
	v_and_b32_sdwa v25, v20, v108 dst_sel:DWORD dst_unused:UNUSED_PAD src0_sel:WORD_1 src1_sel:DWORD
	v_add3_u32 v20, v20, v25, s66
	v_add3_u32 v22, v22, v24, s66
	v_and_b32_sdwa v24, v23, v108 dst_sel:DWORD dst_unused:UNUSED_PAD src0_sel:WORD_1 src1_sel:DWORD
	v_and_b32_sdwa v25, v21, v108 dst_sel:DWORD dst_unused:UNUSED_PAD src0_sel:WORD_1 src1_sel:DWORD
	v_add3_u32 v23, v23, v24, s66
	v_add3_u32 v21, v21, v25, s66
	v_and_b32_e32 v23, 0xffff0000, v23
	v_and_b32_e32 v24, 0xffff0000, v21
	v_or_b32_sdwa v21, v23, v22 dst_sel:DWORD dst_unused:UNUSED_PAD src0_sel:DWORD src1_sel:WORD_1
	v_or_b32_sdwa v20, v24, v20 dst_sel:DWORD dst_unused:UNUSED_PAD src0_sel:DWORD src1_sel:WORD_1
	global_store_dwordx2 v[32:33], v[20:21], off offset:64
	v_and_b32_sdwa v20, v18, v108 dst_sel:DWORD dst_unused:UNUSED_PAD src0_sel:WORD_1 src1_sel:DWORD
	v_and_b32_sdwa v21, v16, v108 dst_sel:DWORD dst_unused:UNUSED_PAD src0_sel:WORD_1 src1_sel:DWORD
	v_add3_u32 v16, v16, v21, s66
	v_add3_u32 v18, v18, v20, s66
	v_and_b32_sdwa v20, v19, v108 dst_sel:DWORD dst_unused:UNUSED_PAD src0_sel:WORD_1 src1_sel:DWORD
	v_and_b32_sdwa v21, v17, v108 dst_sel:DWORD dst_unused:UNUSED_PAD src0_sel:WORD_1 src1_sel:DWORD
	v_add3_u32 v19, v19, v20, s66
	v_add3_u32 v17, v17, v21, s66
	v_and_b32_e32 v19, 0xffff0000, v19
	v_and_b32_e32 v20, 0xffff0000, v17
	v_or_b32_sdwa v17, v19, v18 dst_sel:DWORD dst_unused:UNUSED_PAD src0_sel:DWORD src1_sel:WORD_1
	v_or_b32_sdwa v16, v20, v16 dst_sel:DWORD dst_unused:UNUSED_PAD src0_sel:DWORD src1_sel:WORD_1
	v_and_b32_sdwa v18, v14, v108 dst_sel:DWORD dst_unused:UNUSED_PAD src0_sel:WORD_1 src1_sel:DWORD
	v_and_b32_sdwa v19, v12, v108 dst_sel:DWORD dst_unused:UNUSED_PAD src0_sel:WORD_1 src1_sel:DWORD
	global_store_dwordx2 v[32:33], v[16:17], off offset:96
	v_or_b32_e32 v16, 48, v166
	v_add3_u32 v12, v12, v19, s66
	v_add3_u32 v14, v14, v18, s66
	v_and_b32_sdwa v18, v15, v108 dst_sel:DWORD dst_unused:UNUSED_PAD src0_sel:WORD_1 src1_sel:DWORD
	v_and_b32_sdwa v19, v13, v108 dst_sel:DWORD dst_unused:UNUSED_PAD src0_sel:WORD_1 src1_sel:DWORD
	v_ashrrev_i32_e32 v17, 31, v16
	v_add3_u32 v15, v15, v18, s66
	v_add3_u32 v13, v13, v19, s66
	v_lshlrev_b64 v[16:17], 12, v[16:17]
	v_and_b32_e32 v15, 0xffff0000, v15
	v_and_b32_e32 v18, 0xffff0000, v13
	v_lshl_add_u64 v[16:17], v[198:199], 0, v[16:17]
	v_or_b32_sdwa v13, v15, v14 dst_sel:DWORD dst_unused:UNUSED_PAD src0_sel:DWORD src1_sel:WORD_1
	v_or_b32_sdwa v12, v18, v12 dst_sel:DWORD dst_unused:UNUSED_PAD src0_sel:DWORD src1_sel:WORD_1
	global_store_dwordx2 v[16:17], v[12:13], off
	v_and_b32_sdwa v12, v6, v108 dst_sel:DWORD dst_unused:UNUSED_PAD src0_sel:WORD_1 src1_sel:DWORD
	v_and_b32_sdwa v13, v4, v108 dst_sel:DWORD dst_unused:UNUSED_PAD src0_sel:WORD_1 src1_sel:DWORD
	v_add3_u32 v4, v4, v13, s66
	v_add3_u32 v6, v6, v12, s66
	v_and_b32_sdwa v12, v7, v108 dst_sel:DWORD dst_unused:UNUSED_PAD src0_sel:WORD_1 src1_sel:DWORD
	v_and_b32_sdwa v13, v5, v108 dst_sel:DWORD dst_unused:UNUSED_PAD src0_sel:WORD_1 src1_sel:DWORD
	v_add3_u32 v7, v7, v12, s66
	v_add3_u32 v5, v5, v13, s66
	v_and_b32_e32 v7, 0xffff0000, v7
	v_and_b32_e32 v12, 0xffff0000, v5
	v_or_b32_sdwa v5, v7, v6 dst_sel:DWORD dst_unused:UNUSED_PAD src0_sel:DWORD src1_sel:WORD_1
	v_or_b32_sdwa v4, v12, v4 dst_sel:DWORD dst_unused:UNUSED_PAD src0_sel:DWORD src1_sel:WORD_1
	global_store_dwordx2 v[16:17], v[4:5], off offset:32
	v_and_b32_sdwa v4, v2, v108 dst_sel:DWORD dst_unused:UNUSED_PAD src0_sel:WORD_1 src1_sel:DWORD
	v_and_b32_sdwa v5, v0, v108 dst_sel:DWORD dst_unused:UNUSED_PAD src0_sel:WORD_1 src1_sel:DWORD
	v_add3_u32 v0, v0, v5, s66
	v_add3_u32 v2, v2, v4, s66
	v_and_b32_sdwa v4, v3, v108 dst_sel:DWORD dst_unused:UNUSED_PAD src0_sel:WORD_1 src1_sel:DWORD
	v_and_b32_sdwa v5, v1, v108 dst_sel:DWORD dst_unused:UNUSED_PAD src0_sel:WORD_1 src1_sel:DWORD
	v_add3_u32 v3, v3, v4, s66
	v_add3_u32 v1, v1, v5, s66
	v_and_b32_e32 v3, 0xffff0000, v3
	v_and_b32_e32 v4, 0xffff0000, v1
	v_or_b32_sdwa v1, v3, v2 dst_sel:DWORD dst_unused:UNUSED_PAD src0_sel:DWORD src1_sel:WORD_1
	v_or_b32_sdwa v0, v4, v0 dst_sel:DWORD dst_unused:UNUSED_PAD src0_sel:DWORD src1_sel:WORD_1
	global_store_dwordx2 v[16:17], v[0:1], off offset:64
	v_and_b32_sdwa v1, v8, v108 dst_sel:DWORD dst_unused:UNUSED_PAD src0_sel:WORD_1 src1_sel:DWORD
	v_add3_u32 v2, v8, v1, s66
	v_and_b32_sdwa v1, v11, v108 dst_sel:DWORD dst_unused:UNUSED_PAD src0_sel:WORD_1 src1_sel:DWORD
	v_and_b32_sdwa v3, v9, v108 dst_sel:DWORD dst_unused:UNUSED_PAD src0_sel:WORD_1 src1_sel:DWORD
	v_and_b32_sdwa v0, v10, v108 dst_sel:DWORD dst_unused:UNUSED_PAD src0_sel:WORD_1 src1_sel:DWORD
	v_add3_u32 v1, v11, v1, s66
	v_add3_u32 v3, v9, v3, s66
	v_add3_u32 v0, v10, v0, s66
	v_and_b32_e32 v1, 0xffff0000, v1
	v_and_b32_e32 v3, 0xffff0000, v3
	v_or_b32_sdwa v1, v1, v0 dst_sel:DWORD dst_unused:UNUSED_PAD src0_sel:DWORD src1_sel:WORD_1
	v_or_b32_sdwa v0, v3, v2 dst_sel:DWORD dst_unused:UNUSED_PAD src0_sel:DWORD src1_sel:WORD_1
	global_store_dwordx2 v[16:17], v[0:1], off offset:96
	s_add_i32 s61, s61, s60
	s_cmp_ge_i32 s61, s62
	s_cbranch_scc0 .LBB0_660

.LBB0_725:
	s_cmp_gt_i32 s54, 10
	s_cselect_b64 s[6:7], -1, 0
	s_cmp_lt_i32 s55, 11
	s_cselect_b64 s[8:9], -1, 0
	s_or_b64 s[6:7], s[6:7], s[8:9]
	s_and_b64 vcc, exec, s[6:7]
	s_cbranch_vccnz .LBB0_909
	s_cmpk_gt_i32 s2, 0x7ff
	s_cbranch_scc1 .LBB0_855
	s_load_dwordx2 s[16:17], s[0:1], 0xa0
	s_load_dwordx2 s[18:19], s[0:1], 0xd0
	s_load_dwordx2 s[20:21], s[0:1], 0x108
	v_lshrrev_b32_e32 v59, 4, v168
	v_lshlrev_b32_e32 v0, 3, v168
	v_mov_b32_e32 v53, 0
	v_and_b32_e32 v58, 0x78, v0
	s_waitcnt lgkmcnt(0)
	s_add_u32 s22, s20, 0x800000
	s_addc_u32 s23, s21, 0
	s_and_b32 s9, s2, 7
	s_add_i32 s8, 16, 0x10c00
	s_lshl_b32 s3, s9, 16
	s_add_u32 s6, s18, s3
	v_lshlrev_b32_e32 v52, 8, v59
	s_addc_u32 s7, s19, 0
	v_lshlrev_b32_e32 v2, 1, v58
	v_mov_b32_e32 v3, v53
	v_lshl_add_u64 v[4:5], s[6:7], 0, v[52:53]
	v_lshl_add_u64 v[54:55], v[4:5], 0, v[2:3]
	s_movk_i32 s36, 0x7000
	v_add_co_u32_e32 v28, vcc, s36, v54
	v_lshrrev_b32_e32 v82, 2, v168
	s_lshl_b32 s3, s2, 3
	v_addc_co_u32_e32 v29, vcc, 0, v55, vcc
	s_movk_i32 s37, 0x6000
	v_and_b32_e32 v63, 0xf0, v82
	s_and_b32 s6, s3, 0xffffffc0
	v_add_co_u32_e32 v30, vcc, s37, v54
	v_add_u32_e32 v1, s6, v63
	s_nop 0
	v_addc_co_u32_e32 v31, vcc, 0, v55, vcc
	s_movk_i32 s6, 0x5000
	v_add_co_u32_e32 v36, vcc, s6, v54
	v_and_b32_e32 v71, 15, v168
	s_nop 0
	v_addc_co_u32_e32 v37, vcc, 0, v55, vcc
	s_movk_i32 s38, 0x4000
	v_or_b32_e32 v4, v1, v71
	v_add_co_u32_e32 v38, vcc, s38, v54
	v_ashrrev_i32_e32 v5, 31, v4
	s_nop 0
	v_addc_co_u32_e32 v39, vcc, 0, v55, vcc
	s_movk_i32 s6, 0x3000
	v_lshlrev_b64 v[4:5], 12, v[4:5]
	v_add_co_u32_e32 v44, vcc, s6, v54
	v_bfe_u32 v61, v168, 4, 2
	s_mov_b32 s25, 0
	v_lshl_add_u64 v[4:5], s[16:17], 0, v[4:5]
	s_lshl_b32 s24, s9, 9
	v_addc_co_u32_e32 v45, vcc, 0, v55, vcc
	s_movk_i32 s39, 0x2000
	v_lshlrev_b32_e32 v0, 4, v61
	v_lshl_add_u64 v[4:5], v[4:5], 0, s[24:25]
	v_mov_b32_e32 v1, v53
	v_add_co_u32_e32 v46, vcc, s39, v54
	v_lshl_add_u64 v[20:21], v[4:5], 0, v[0:1]
	s_nop 0
	v_addc_co_u32_e32 v47, vcc, 0, v55, vcc
	s_movk_i32 s6, 0x1000
	global_load_dwordx4 v[4:7], v[20:21], off offset:192
	global_load_dwordx4 v[8:11], v[20:21], off offset:128
	global_load_dwordx4 v[12:15], v[20:21], off offset:64
	global_load_dwordx4 v[16:19], v[20:21], off
	v_add_co_u32_e32 v56, vcc, s6, v54
	global_load_dwordx4 v[24:27], v[28:29], off
	global_load_dwordx4 v[20:23], v[30:31], off
	v_addc_co_u32_e32 v57, vcc, 0, v55, vcc
	global_load_dwordx4 v[32:35], v[36:37], off
	global_load_dwordx4 v[28:31], v[38:39], off
	global_load_dwordx4 v[40:43], v[44:45], off
	s_nop 0
	global_load_dwordx4 v[36:39], v[46:47], off
	s_nop 0
	global_load_dwordx4 v[44:47], v[56:57], off
	global_load_dwordx4 v[48:51], v[54:55], off
	v_mbcnt_lo_u32_b32 v1, -1, 0
	v_lshl_add_u64 v[54:55], s[18:19], 0, v[52:53]
	v_mbcnt_hi_u32_b32 v1, -1, v1
	v_lshl_add_u64 v[54:55], v[54:55], 0, v[2:3]
	v_and_b32_e32 v3, 64, v1
	v_add_u32_e32 v64, 16, v2
	v_xor_b32_e32 v2, 1, v1
	v_add_u32_e32 v3, 64, v3
	v_cmp_lt_i32_e32 vcc, v2, v3
	v_and_b32_e32 v83, 3, v168
	s_movk_i32 s9, 0x110
	v_cndmask_b32_e32 v2, v1, v2, vcc
	v_lshlrev_b32_e32 v96, 2, v2
	v_xor_b32_e32 v2, 2, v1
	v_add_u32_e32 v65, 16, v0
	v_lshl_or_b32 v0, v61, 2, v63
	s_movk_i32 s6, 0x210
	v_cmp_lt_i32_e32 vcc, v2, v3
	v_lshlrev_b32_e32 v60, 7, v59
	v_lshlrev_b32_e32 v62, 3, v61
	v_or_b32_e32 v84, v63, v71
	v_mul_u32_u24_e32 v59, 0x110, v59
	v_mad_u32_u24 v85, v82, s6, 16
	v_mul_u32_u24_e32 v61, 0x110, v71
	v_mad_u32_u24 v88, v71, s9, v65
	v_lshl_add_u32 v63, v71, 2, 16
	v_mul_u32_u24_e32 v66, 0x210, v0
	v_lshlrev_b32_e32 v0, 4, v83
	v_cndmask_b32_e32 v1, v1, v2, vcc
	v_lshl_add_u32 v86, v82, 5, s8
	v_lshl_add_u32 v87, v83, 7, v85
	v_cmp_eq_u32_e64 s[6:7], 2, v83
	v_add_u32_e32 v89, 0x1100, v88
	v_add_u32_e32 v90, 0x2200, v88
	v_add_u32_e32 v91, 0x3300, v88
	v_add_u32_e32 v92, 0x4400, v88
	v_add_u32_e32 v93, 0x5500, v88
	v_add_u32_e32 v94, 0x6600, v88
	v_add_u32_e32 v95, 0x7700, v88
	v_cmp_eq_u32_e64 s[8:9], 3, v83
	v_cmp_ne_u32_e64 s[10:11], 3, v83
	v_cmp_gt_u32_e64 s[12:13], 2, v83
	v_cmp_eq_u32_e64 s[14:15], 0, v83
	v_lshlrev_b32_e32 v97, 2, v1
	v_mov_b32_e32 v1, v0
	v_mov_b32_e32 v2, v0
	v_mov_b32_e32 v3, v0
	v_mov_b32_e32 v56, v0
	v_mov_b32_e32 v57, v0
	s_lshl_b32 s40, s2, 4
	s_lshl_b32 s41, s52, 4
	s_lshl_b32 s42, s52, 3
	s_movk_i32 s43, 0xff80
	s_movk_i32 s44, 0x7f
	s_movk_i32 s45, 0x6f
	s_movk_i32 s48, 0x5f
	s_movk_i32 s49, 0x4f
	v_lshlrev_b32_e32 v52, 1, v60
	v_lshlrev_b32_e32 v58, 1, v58
	s_mov_b32 s50, 0x9000
	s_mov_b32 s51, 0xb000
	s_mov_b32 s56, 0xd000
	s_mov_b32 s57, 0xf000
	v_lshlrev_b32_e32 v60, 1, v62
	s_movk_i32 s58, 0xff00
	v_add_u32_e32 v98, v64, v59
	v_add_u32_e32 v99, v65, v61
	v_add_u32_e32 v100, v63, v66
	v_bfrev_b32_e32 v101, 1
	s_mov_b32 s59, s2
	s_mov_b32 s80, s2
	s_load_dwordx2 s[88:89], s[0:1], 0x88
	s_load_dwordx2 s[96:97], s[0:1], 0x90
	s_load_dwordx2 s[98:99], s[0:1], 0xf8
	v_lshlrev_b32_e32 v234, 4, v168
	v_lshlrev_b32_e32 v235, 2, v168
	s_waitcnt lgkmcnt(0)
	s_branch .LBB0_729
.LBB0_728:
	s_or_b64 exec, exec, s[28:29]
	s_add_i32 s80, s80, s52
	s_add_i32 s40, s40, s41
	s_andn2_b64 vcc, exec, s[26:27]
	s_add_i32 s3, s3, s42
	s_cbranch_vccz .LBB0_855
.LBB0_729:
	s_waitcnt vmcnt(0)
	s_barrier
	ds_write_b128 v98, v[48:51]
	ds_write_b128 v98, v[44:47] offset:4352
	ds_write_b128 v98, v[36:39] offset:8704
	ds_write_b128 v98, v[40:43] offset:13056
	ds_write_b128 v98, v[28:31] offset:17408
	ds_write_b128 v98, v[32:35] offset:21760
	ds_write_b128 v98, v[20:23] offset:26112
	ds_write_b128 v98, v[24:27] offset:30464
	s_waitcnt lgkmcnt(0)
	s_barrier
	ds_read_b128 v[20:23], v99
	ds_read_b128 v[24:27], v99 offset:4352
	ds_read_b128 v[28:31], v99 offset:8704
	ds_read_b128 v[32:35], v99 offset:13056
	ds_read_b128 v[36:39], v99 offset:17408
	ds_read_b128 v[40:43], v99 offset:21760
	ds_read_b128 v[44:47], v99 offset:26112
	ds_read_b128 v[48:51], v99 offset:30464
	s_waitcnt lgkmcnt(7)
	v_mfma_f32_16x16x32_bf16 v[20:23], v[16:19], v[20:23], 0
	s_and_b32 s24, s59, 7
	s_lshl_b32 s26, s24, 16
	s_add_u32 s26, s18, s26
	s_waitcnt lgkmcnt(6)
	v_mfma_f32_16x16x32_bf16 v[24:27], v[16:19], v[24:27], 0
	s_addc_u32 s27, s19, 0
	s_and_b32 s34, s3, 0xffffffc0
	s_lshl_b32 s24, s24, 9
	s_waitcnt lgkmcnt(5)
	v_mfma_f32_16x16x32_bf16 v[28:31], v[16:19], v[28:31], 0
	s_waitcnt lgkmcnt(4)
	v_mfma_f32_16x16x32_bf16 v[32:35], v[16:19], v[32:35], 0
	s_waitcnt lgkmcnt(3)
	v_mfma_f32_16x16x32_bf16 v[36:39], v[16:19], v[36:39], 0
	s_waitcnt lgkmcnt(2)
	v_mfma_f32_16x16x32_bf16 v[40:43], v[16:19], v[40:43], 0
	s_waitcnt lgkmcnt(1)
	v_mfma_f32_16x16x32_bf16 v[44:47], v[16:19], v[44:47], 0
	s_waitcnt lgkmcnt(0)
	v_mfma_f32_16x16x32_bf16 v[16:19], v[16:19], v[48:51], 0
	ds_read_b128 v[48:51], v88 offset:64
	ds_read_b128 v[62:65], v88 offset:128
	s_waitcnt lgkmcnt(1)
	v_mfma_f32_16x16x32_bf16 v[20:23], v[12:15], v[48:51], v[20:23]
	ds_read_b128 v[48:51], v89 offset:64
	ds_read_b128 v[66:69], v88 offset:192
	s_waitcnt lgkmcnt(2)
	v_mfma_f32_16x16x32_bf16 v[20:23], v[8:11], v[62:65], v[20:23]
	s_waitcnt lgkmcnt(1)
	v_mfma_f32_16x16x32_bf16 v[24:27], v[12:15], v[48:51], v[24:27]
	ds_read_b128 v[48:51], v90 offset:64
	ds_read_b128 v[72:75], v91 offset:64
	ds_read_b128 v[76:79], v90 offset:128
	s_waitcnt lgkmcnt(2)
	v_mfma_f32_16x16x32_bf16 v[28:31], v[12:15], v[48:51], v[28:31]
	ds_read_b128 v[48:51], v92 offset:64
	ds_read_b128 v[102:105], v92 offset:128
	ds_read_b128 v[106:109], v90 offset:192
	v_mfma_f32_16x16x32_bf16 v[20:23], v[4:7], v[66:69], v[20:23]
	s_waitcnt lgkmcnt(4)
	v_mfma_f32_16x16x32_bf16 v[32:35], v[12:15], v[72:75], v[32:35]
	ds_read_b128 v[72:75], v94 offset:64
	ds_read_b128 v[110:113], v94 offset:128
	ds_read_b128 v[114:117], v89 offset:128
	ds_read_b128 v[118:121], v89 offset:192
	s_nop 1
	v_not_b32_e32 v59, v20
	v_or_b32_e32 v61, 0x80000000, v20
	s_waitcnt lgkmcnt(6)
	v_mfma_f32_16x16x32_bf16 v[36:39], v[12:15], v[48:51], v[36:39]
	ds_read_b128 v[48:51], v91 offset:128
	ds_read_b128 v[122:125], v91 offset:192
	ds_read_b128 v[126:129], v93 offset:64
	ds_read_b128 v[130:133], v92 offset:192
	ds_read_b128 v[62:65], v93 offset:128
	ds_read_b128 v[134:137], v93 offset:192
	ds_read_b128 v[138:141], v95 offset:64
	ds_read_b128 v[146:149], v94 offset:192
	v_cmp_gt_i32_e32 vcc, 0, v20
	s_waitcnt lgkmcnt(5)
	v_mfma_f32_16x16x32_bf16 v[40:43], v[12:15], v[126:129], v[40:43]
	v_cndmask_b32_e32 v20, v61, v59, vcc
	v_and_b32_e32 v20, 0xffffff80, v20
	v_bitop3_b32 v59, v71, s44, v20 bitop3:0x36
	v_mfma_f32_16x16x32_bf16 v[44:47], v[12:15], v[72:75], v[44:47]
	v_not_b32_e32 v20, v21
	v_cmp_gt_i32_e32 vcc, 0, v21
	ds_read_b128 v[66:69], v95 offset:128
	ds_read_b128 v[150:153], v95 offset:192
	s_waitcnt lgkmcnt(3)
	v_mfma_f32_16x16x32_bf16 v[12:15], v[12:15], v[138:141], v[16:19]
	s_nop 2
	v_or_b32_e32 v16, 0x80000000, v21
	v_cndmask_b32_e32 v20, v16, v20, vcc
	v_mfma_f32_16x16x32_bf16 v[16:19], v[8:11], v[114:117], v[24:27]
	v_and_b32_e32 v20, 0xffffff80, v20
	v_bitop3_b32 v61, v71, s44, v20 bitop3:0x36
	v_not_b32_e32 v20, v22
	v_or_b32_e32 v21, 0x80000000, v22
	v_cmp_gt_i32_e32 vcc, 0, v22
	v_mfma_f32_16x16x32_bf16 v[16:19], v[4:7], v[118:121], v[16:19]
	s_nop 0
	v_cndmask_b32_e32 v20, v21, v20, vcc
	v_and_b32_e32 v20, 0xffffff80, v20
	v_mfma_f32_16x16x32_bf16 v[24:27], v[8:11], v[76:79], v[28:31]
	v_or_b32_e32 v21, 0x80000000, v23
	v_cmp_gt_i32_e32 vcc, 0, v23
	v_add_u32_e32 v77, 0x8800, v100
	v_mfma_f32_16x16x32_bf16 v[28:31], v[8:11], v[48:51], v[32:35]
	v_bitop3_b32 v48, v71, s44, v20 bitop3:0x36
	v_not_b32_e32 v20, v23
	v_cndmask_b32_e32 v20, v21, v20, vcc
	v_mfma_f32_16x16x32_bf16 v[32:35], v[8:11], v[102:105], v[36:39]
	v_cmp_gt_i32_e32 vcc, 0, v16
	v_and_b32_e32 v20, 0xffffff80, v20
	v_bitop3_b32 v49, v71, s44, v20 bitop3:0x36
	v_not_b32_e32 v36, v16
	v_or_b32_e32 v37, 0x80000000, v16
	v_cndmask_b32_e32 v16, v37, v36, vcc
	v_and_b32_e32 v16, 0xffffff80, v16
	v_bitop3_b32 v16, v71, s45, v16 bitop3:0x36
	v_mfma_f32_16x16x32_bf16 v[20:23], v[8:11], v[62:65], v[40:43]
	ds_write2_b32 v77, v59, v16 offset1:16
	v_not_b32_e32 v16, v17
	v_cmp_gt_i32_e32 vcc, 0, v17
	v_or_b32_e32 v40, 0x80000000, v17
	v_or_b32_e32 v17, 0x80000000, v18
	v_cndmask_b32_e32 v16, v40, v16, vcc
	v_and_b32_e32 v16, 0xffffff80, v16
	v_bitop3_b32 v16, v71, s45, v16 bitop3:0x36
	ds_write2_b32 v77, v61, v16 offset0:132 offset1:148
	v_not_b32_e32 v16, v18
	v_cmp_gt_i32_e32 vcc, 0, v18
	v_mfma_f32_16x16x32_bf16 v[36:39], v[8:11], v[110:113], v[44:47]
	v_add_u32_e32 v78, 0x8c00, v100
	v_cndmask_b32_e32 v16, v17, v16, vcc
	v_and_b32_e32 v16, 0xffffff80, v16
	s_waitcnt lgkmcnt(3)
	v_mfma_f32_16x16x32_bf16 v[8:11], v[8:11], v[66:69], v[12:15]
	v_bitop3_b32 v16, v71, s45, v16 bitop3:0x36
	ds_write2_b32 v78, v48, v16 offset0:8 offset1:24
	v_not_b32_e32 v16, v19
	v_mfma_f32_16x16x32_bf16 v[12:15], v[4:7], v[106:109], v[24:27]
	v_or_b32_e32 v17, 0x80000000, v19
	v_cmp_gt_i32_e32 vcc, 0, v19
	v_mov_b32_e32 v59, v53
	v_mfma_f32_16x16x32_bf16 v[24:27], v[4:7], v[122:125], v[28:31]
	v_mov_b32_e32 v61, v53
	v_mfma_f32_16x16x32_bf16 v[28:31], v[4:7], v[130:133], v[32:35]
	v_mfma_f32_16x16x32_bf16 v[20:23], v[4:7], v[134:137], v[20:23]
	v_mfma_f32_16x16x32_bf16 v[32:35], v[4:7], v[146:149], v[36:39]
	s_waitcnt lgkmcnt(3)
	v_mfma_f32_16x16x32_bf16 v[4:7], v[4:7], v[150:153], v[8:11]
	s_nop 2
	v_cndmask_b32_e32 v8, v17, v16, vcc
	v_and_b32_e32 v8, 0xffffff80, v8
	v_bitop3_b32 v8, v71, s45, v8 bitop3:0x36
	ds_write2_b32 v78, v49, v8 offset0:140 offset1:156
	v_not_b32_e32 v8, v12
	v_or_b32_e32 v9, 0x80000000, v12
	v_cmp_gt_i32_e32 vcc, 0, v12
	v_or_b32_e32 v10, 0x80000000, v13
	v_or_b32_e32 v11, 0x80000000, v14
	v_cndmask_b32_e32 v8, v9, v8, vcc
	v_not_b32_e32 v9, v13
	v_cmp_gt_i32_e32 vcc, 0, v13
	v_or_b32_e32 v12, 0x80000000, v15
	v_or_b32_e32 v13, 0x80000000, v24
	v_cndmask_b32_e32 v9, v10, v9, vcc
	v_not_b32_e32 v10, v14
	v_cmp_gt_i32_e32 vcc, 0, v14
	v_and_b32_e32 v8, 0xffffff80, v8
	v_bitop3_b32 v8, v71, s48, v8 bitop3:0x36
	v_cndmask_b32_e32 v10, v11, v10, vcc
	v_not_b32_e32 v11, v15
	v_cmp_gt_i32_e32 vcc, 0, v15
	v_and_b32_e32 v9, 0xffffff80, v9
	v_bitop3_b32 v9, v71, s48, v9 bitop3:0x36
	v_cndmask_b32_e32 v11, v12, v11, vcc
	v_not_b32_e32 v12, v24
	v_cmp_gt_i32_e32 vcc, 0, v24
	v_and_b32_e32 v10, 0xffffff80, v10
	v_bitop3_b32 v10, v71, s48, v10 bitop3:0x36
	v_cndmask_b32_e32 v12, v13, v12, vcc
	v_and_b32_e32 v12, 0xffffff80, v12
	v_bitop3_b32 v12, v71, s49, v12 bitop3:0x36
	ds_write2_b32 v77, v8, v12 offset0:32 offset1:48
	v_not_b32_e32 v8, v25
	v_or_b32_e32 v12, 0x80000000, v25
	v_cmp_gt_i32_e32 vcc, 0, v25
	v_and_b32_e32 v11, 0xffffff80, v11
	v_bitop3_b32 v11, v71, s48, v11 bitop3:0x36
	v_cndmask_b32_e32 v8, v12, v8, vcc
	v_and_b32_e32 v8, 0xffffff80, v8
	v_bitop3_b32 v8, v71, s49, v8 bitop3:0x36
	ds_write2_b32 v77, v9, v8 offset0:164 offset1:180
	v_not_b32_e32 v8, v26
	v_or_b32_e32 v9, 0x80000000, v26
	v_cmp_gt_i32_e32 vcc, 0, v26
	v_or_b32_e32 v12, 0x80000000, v31
	v_or_b32_e32 v13, 0x80000000, v20
	v_cndmask_b32_e32 v8, v9, v8, vcc
	v_and_b32_e32 v8, 0xffffff80, v8
	v_bitop3_b32 v8, v71, s49, v8 bitop3:0x36
	ds_write2_b32 v78, v10, v8 offset0:40 offset1:56
	v_not_b32_e32 v8, v27
	v_or_b32_e32 v9, 0x80000000, v27
	v_cmp_gt_i32_e32 vcc, 0, v27
	v_or_b32_e32 v10, 0x80000000, v29
	s_nop 0
	v_cndmask_b32_e32 v8, v9, v8, vcc
	v_and_b32_e32 v8, 0xffffff80, v8
	v_bitop3_b32 v8, v71, s49, v8 bitop3:0x36
	ds_write2_b32 v78, v11, v8 offset0:172 offset1:188
	v_not_b32_e32 v8, v28
	v_or_b32_e32 v9, 0x80000000, v28
	v_cmp_gt_i32_e32 vcc, 0, v28
	v_or_b32_e32 v11, 0x80000000, v30
	s_nop 0
	v_cndmask_b32_e32 v8, v9, v8, vcc
	v_not_b32_e32 v9, v29
	v_cmp_gt_i32_e32 vcc, 0, v29
	v_and_b32_e32 v8, 0xffffff80, v8
	v_bitop3_b32 v8, v71, 63, v8 bitop3:0x36
	v_cndmask_b32_e32 v9, v10, v9, vcc
	v_not_b32_e32 v10, v30
	v_cmp_gt_i32_e32 vcc, 0, v30
	v_and_b32_e32 v9, 0xffffff80, v9
	v_bitop3_b32 v9, v71, 63, v9 bitop3:0x36
	v_cndmask_b32_e32 v10, v11, v10, vcc
	v_not_b32_e32 v11, v31
	v_cmp_gt_i32_e32 vcc, 0, v31
	v_and_b32_e32 v10, 0xffffff80, v10
	v_bitop3_b32 v10, v71, 63, v10 bitop3:0x36
	v_cndmask_b32_e32 v11, v12, v11, vcc
	v_not_b32_e32 v12, v20
	v_cmp_gt_i32_e32 vcc, 0, v20
	v_and_b32_e32 v11, 0xffffff80, v11
	v_bitop3_b32 v11, v71, 63, v11 bitop3:0x36
	v_cndmask_b32_e32 v12, v13, v12, vcc
	v_and_b32_e32 v12, 0xffffff80, v12
	v_bitop3_b32 v12, v71, 47, v12 bitop3:0x36
	ds_write2_b32 v77, v8, v12 offset0:64 offset1:80
	v_not_b32_e32 v8, v21
	v_or_b32_e32 v12, 0x80000000, v21
	v_cmp_gt_i32_e32 vcc, 0, v21
	v_or_b32_e32 v13, 0x80000000, v4
	s_nop 0
	v_cndmask_b32_e32 v8, v12, v8, vcc
	v_and_b32_e32 v8, 0xffffff80, v8
	v_bitop3_b32 v8, v71, 47, v8 bitop3:0x36
	ds_write2_b32 v77, v9, v8 offset0:196 offset1:212
	v_not_b32_e32 v8, v22
	v_or_b32_e32 v9, 0x80000000, v22
	v_cmp_gt_i32_e32 vcc, 0, v22
	v_or_b32_e32 v12, 0x80000000, v35
	s_nop 0
	v_cndmask_b32_e32 v8, v9, v8, vcc
	v_and_b32_e32 v8, 0xffffff80, v8
	v_bitop3_b32 v8, v71, 47, v8 bitop3:0x36
	ds_write2_b32 v78, v10, v8 offset0:72 offset1:88
	v_not_b32_e32 v8, v23
	v_or_b32_e32 v9, 0x80000000, v23
	v_cmp_gt_i32_e32 vcc, 0, v23
	v_or_b32_e32 v10, 0x80000000, v33
	s_nop 0
	v_cndmask_b32_e32 v8, v9, v8, vcc
	v_and_b32_e32 v8, 0xffffff80, v8
	v_bitop3_b32 v8, v71, 47, v8 bitop3:0x36
	ds_write2_b32 v78, v11, v8 offset0:204 offset1:220
	v_not_b32_e32 v8, v32
	v_or_b32_e32 v9, 0x80000000, v32
	v_cmp_gt_i32_e32 vcc, 0, v32
	v_or_b32_e32 v11, 0x80000000, v34
	s_nop 0
	v_cndmask_b32_e32 v8, v9, v8, vcc
	v_not_b32_e32 v9, v33
	v_cmp_gt_i32_e32 vcc, 0, v33
	v_and_b32_e32 v8, 0xffffff80, v8
	v_bitop3_b32 v8, v71, 31, v8 bitop3:0x36
	v_cndmask_b32_e32 v9, v10, v9, vcc
	v_not_b32_e32 v10, v34
	v_cmp_gt_i32_e32 vcc, 0, v34
	v_and_b32_e32 v9, 0xffffff80, v9
	v_bitop3_b32 v9, v71, 31, v9 bitop3:0x36
	v_cndmask_b32_e32 v10, v11, v10, vcc
	v_not_b32_e32 v11, v35
	v_cmp_gt_i32_e32 vcc, 0, v35
	v_and_b32_e32 v10, 0xffffff80, v10
	v_bitop3_b32 v10, v71, 31, v10 bitop3:0x36
	v_cndmask_b32_e32 v11, v12, v11, vcc
	v_not_b32_e32 v12, v4
	v_cmp_gt_i32_e32 vcc, 0, v4
	v_and_b32_e32 v11, 0xffffff80, v11
	v_bitop3_b32 v11, v71, 31, v11 bitop3:0x36
	v_cndmask_b32_e32 v4, v13, v12, vcc
	v_and_b32_e32 v4, 0xffffff80, v4
	v_bitop3_b32 v4, v71, 15, v4 bitop3:0x36
	ds_write2_b32 v77, v8, v4 offset0:96 offset1:112
	v_not_b32_e32 v4, v5
	v_or_b32_e32 v8, 0x80000000, v5
	v_cmp_gt_i32_e32 vcc, 0, v5
	v_or_b32_e32 v5, 0x80000000, v6
	s_nop 0
	v_cndmask_b32_e32 v4, v8, v4, vcc
	v_and_b32_e32 v4, 0xffffff80, v4
	v_bitop3_b32 v4, v71, 15, v4 bitop3:0x36
	ds_write2_b32 v77, v9, v4 offset0:228 offset1:244
	v_not_b32_e32 v4, v6
	v_cmp_gt_i32_e32 vcc, 0, v6
	s_nop 1
	v_cndmask_b32_e32 v4, v5, v4, vcc
	v_and_b32_e32 v4, 0xffffff80, v4
	v_bitop3_b32 v4, v71, 15, v4 bitop3:0x36
	ds_write2_b32 v78, v10, v4 offset0:104 offset1:120
	v_not_b32_e32 v4, v7
	v_or_b32_e32 v5, 0x80000000, v7
	v_cmp_gt_i32_e32 vcc, 0, v7
	s_nop 1
	v_cndmask_b32_e32 v4, v5, v4, vcc
	v_and_b32_e32 v4, 0xffffff80, v4
	v_bitop3_b32 v4, v71, 15, v4 bitop3:0x36
	ds_write2_b32 v78, v11, v4 offset0:236 offset1:252
	v_lshl_add_u64 v[4:5], s[26:27], 0, v[52:53]
	v_lshl_add_u64 v[4:5], v[4:5], 0, v[58:59]
	v_add_co_u32_e32 v6, vcc, s50, v4
	s_waitcnt lgkmcnt(0)
	s_nop 0
	v_addc_co_u32_e32 v7, vcc, 0, v5, vcc
	s_barrier
	global_load_dwordx4 v[16:19], v[6:7], off offset:-4096
	global_load_dwordx4 v[20:23], v[6:7], off
	v_add_co_u32_e32 v6, vcc, s51, v4
	s_nop 1
	v_addc_co_u32_e32 v7, vcc, 0, v5, vcc
	global_load_dwordx4 v[24:27], v[6:7], off offset:-4096
	global_load_dwordx4 v[28:31], v[6:7], off
	v_add_co_u32_e32 v6, vcc, s56, v4
	s_nop 1
	v_addc_co_u32_e32 v7, vcc, 0, v5, vcc
	v_add_co_u32_e32 v4, vcc, s57, v4
	global_load_dwordx4 v[36:39], v[6:7], off offset:-4096
	global_load_dwordx4 v[40:43], v[6:7], off
	v_addc_co_u32_e32 v5, vcc, 0, v5, vcc
	global_load_dwordx4 v[44:47], v[4:5], off offset:-4096
	global_load_dwordx4 v[48:51], v[4:5], off
	v_add_u32_e32 v4, s34, v84
	v_ashrrev_i32_e32 v5, 31, v4
	v_lshlrev_b64 v[4:5], 12, v[4:5]
	v_lshl_add_u64 v[4:5], s[16:17], 0, v[4:5]
	v_lshl_add_u64 v[4:5], v[4:5], 0, s[24:25]
	v_lshl_add_u64 v[4:5], v[4:5], 0, v[60:61]
	global_load_dwordx4 v[32:35], v[4:5], off offset:256
	global_load_dwordx4 v[12:15], v[4:5], off offset:320
	global_load_dwordx4 v[8:11], v[4:5], off offset:384
	s_nop 0
	global_load_dwordx4 v[4:7], v[4:5], off offset:448
	s_and_b32 s81, s80, 0x3ff
	s_lshl_b32 s81, s81, 16
	s_cmp_lt_u32 s80, 0x400
	s_cselect_b32 s82, s88, s96
	s_cselect_b32 s83, s89, s97
	s_mov_b32 s86, 0x42800000
	s_cselect_b32 s86, 0x43800000, s86
	s_cselect_b32 s87, 0, 0x400
	s_add_u32 s82, s82, s81
	s_addc_u32 s83, s83, 0
	s_lshr_b32 s81, s81, 1
	s_add_u32 s81, s81, s87
	s_add_u32 s84, s98, s81
	s_addc_u32 s85, s99, 0
	global_load_dwordx4 v[170:173], v234, s[82:83]
	s_add_u32 s82, s82, 0x1000
	s_addc_u32 s83, s83, 0
	global_load_dwordx4 v[174:177], v234, s[82:83]
	s_add_u32 s82, s82, 0x1000
	s_addc_u32 s83, s83, 0
	global_load_dwordx4 v[178:181], v234, s[82:83]
	s_add_u32 s82, s82, 0x1000
	s_addc_u32 s83, s83, 0
	global_load_dwordx4 v[182:185], v234, s[82:83]
	s_add_u32 s82, s82, 0x1000
	s_addc_u32 s83, s83, 0
	global_load_dwordx4 v[186:189], v234, s[82:83]
	s_add_u32 s82, s82, 0x1000
	s_addc_u32 s83, s83, 0
	global_load_dwordx4 v[190:193], v234, s[82:83]
	s_add_u32 s82, s82, 0x1000
	s_addc_u32 s83, s83, 0
	global_load_dwordx4 v[194:197], v234, s[82:83]
	s_add_u32 s82, s82, 0x1000
	s_addc_u32 s83, s83, 0
	global_load_dwordx4 v[198:201], v234, s[82:83]
	s_add_u32 s82, s82, 0x1000
	s_addc_u32 s83, s83, 0
	global_load_dwordx4 v[202:205], v234, s[82:83]
	s_add_u32 s82, s82, 0x1000
	s_addc_u32 s83, s83, 0
	global_load_dwordx4 v[206:209], v234, s[82:83]
	s_add_u32 s82, s82, 0x1000
	s_addc_u32 s83, s83, 0
	global_load_dwordx4 v[210:213], v234, s[82:83]
	s_add_u32 s82, s82, 0x1000
	s_addc_u32 s83, s83, 0
	global_load_dwordx4 v[214:217], v234, s[82:83]
	s_add_u32 s82, s82, 0x1000
	s_addc_u32 s83, s83, 0
	global_load_dwordx4 v[218:221], v234, s[82:83]
	s_add_u32 s82, s82, 0x1000
	s_addc_u32 s83, s83, 0
	global_load_dwordx4 v[222:225], v234, s[82:83]
	s_add_u32 s82, s82, 0x1000
	s_addc_u32 s83, s83, 0
	global_load_dwordx4 v[226:229], v234, s[82:83]
	s_add_u32 s82, s82, 0x1000
	s_addc_u32 s83, s83, 0
	global_load_dwordx4 v[230:233], v234, s[82:83]
	ds_read_b128 v[62:65], v87 offset:34816
	ds_read_b128 v[66:69], v87 offset:34832
	ds_read_b128 v[72:75], v87 offset:34848
	ds_read_b128 v[102:105], v87 offset:34864
	s_waitcnt lgkmcnt(3)
	v_max_u32_e32 v59, v62, v63
	s_waitcnt lgkmcnt(2)
	v_max_u32_e32 v62, v68, v69
	v_max_u32_e32 v61, v64, v65
	v_max3_u32 v62, v66, v67, v62
	v_max3_u32 v59, v59, v61, v62
	ds_read_b128 v[62:65], v87 offset:34880
	s_waitcnt lgkmcnt(2)
	v_max_u32_e32 v61, v74, v75
	s_waitcnt lgkmcnt(1)
	v_max_u32_e32 v66, v104, v105
	v_max3_u32 v61, v72, v73, v61
	v_max3_u32 v70, v102, v103, v66
	ds_read_b128 v[66:69], v87 offset:34896
	v_max3_u32 v59, v59, v61, v70
	s_waitcnt lgkmcnt(1)
	v_max_u32_e32 v61, v64, v65
	v_max3_u32 v61, v62, v63, v61
	ds_read_b128 v[62:65], v87 offset:34912
	ds_read_b128 v[72:75], v87 offset:34928
	s_waitcnt lgkmcnt(2)
	v_max_u32_e32 v68, v68, v69
	v_max3_u32 v66, v66, v67, v68
	v_max3_u32 v59, v59, v61, v66
	s_waitcnt lgkmcnt(1)
	v_max_u32_e32 v61, v64, v65
	v_max3_u32 v61, v62, v63, v61
	s_waitcnt lgkmcnt(0)
	v_max_u32_e32 v62, v74, v75
	v_max3_u32 v62, v72, v73, v62
	v_max3_u32 v61, v59, v61, v62
	ds_bpermute_b32 v59, v96, v61
	s_waitcnt lgkmcnt(0)
	v_max_u32_e32 v59, v61, v59
	ds_bpermute_b32 v62, v97, v59
	s_waitcnt lgkmcnt(0)
	v_max_u32_e32 v64, v59, v62
	v_not_b32_e32 v59, v64
	v_bfe_u32 v59, v59, 5, 2
	v_cmp_eq_u32_e32 vcc, v59, v83
	s_and_saveexec_b64 s[26:27], vcc
	s_cbranch_execz .LBB0_731
	v_bitop3_b32 v59, v64, s44, v64 bitop3:0xc
	v_lshl_add_u32 v61, v59, 2, v85
	ds_write_b32 v61, v53 offset:34816
	ds_write_b8 v86, v59
	ds_read_b128 v[66:69], v87 offset:34816
	ds_read_b128 v[72:75], v87 offset:34832
	ds_read_b128 v[102:105], v87 offset:34848
	ds_read_b128 v[106:109], v87 offset:34864
	ds_read_b128 v[110:113], v87 offset:34880
	ds_read_b128 v[114:117], v87 offset:34896
	ds_read_b128 v[118:121], v87 offset:34912
	ds_read_b128 v[122:125], v87 offset:34928
	s_waitcnt lgkmcnt(6)
	v_max_u32_e32 v62, v74, v75
	v_max_u32_e32 v59, v66, v67
	v_max_u32_e32 v61, v68, v69
	v_max3_u32 v62, v72, v73, v62
	v_max3_u32 v59, v59, v61, v62
	s_waitcnt lgkmcnt(5)
	v_max_u32_e32 v61, v104, v105
	s_waitcnt lgkmcnt(4)
	v_max_u32_e32 v62, v108, v109
	v_max3_u32 v61, v102, v103, v61
	v_max3_u32 v62, v106, v107, v62
	v_max3_u32 v59, v59, v61, v62
	s_waitcnt lgkmcnt(3)
	v_max_u32_e32 v61, v112, v113
	s_waitcnt lgkmcnt(2)
	v_max_u32_e32 v62, v116, v117
	v_max3_u32 v61, v110, v111, v61
	v_max3_u32 v62, v114, v115, v62
	v_max3_u32 v59, v59, v61, v62
	s_waitcnt lgkmcnt(1)
	v_max_u32_e32 v61, v120, v121
	s_waitcnt lgkmcnt(0)
	v_max_u32_e32 v62, v124, v125
	v_max3_u32 v61, v118, v119, v61
	v_max3_u32 v62, v122, v123, v62
	v_max3_u32 v61, v59, v61, v62

.LBB0_761:
	s_or_b64 exec, exec, s[26:27]
	s_waitcnt lgkmcnt(0)
	s_barrier
	s_waitcnt vmcnt(27)
	ds_write_b128 v98, v[16:19]
	s_waitcnt vmcnt(26)
	ds_write_b128 v98, v[20:23] offset:4352
	s_waitcnt vmcnt(25)
	ds_write_b128 v98, v[24:27] offset:8704
	s_waitcnt vmcnt(24)
	ds_write_b128 v98, v[28:31] offset:13056
	s_waitcnt vmcnt(23)
	ds_write_b128 v98, v[36:39] offset:17408
	s_waitcnt vmcnt(22)
	ds_write_b128 v98, v[40:43] offset:21760
	s_waitcnt vmcnt(21)
	ds_write_b128 v98, v[44:47] offset:26112
	s_waitcnt vmcnt(20)
	ds_write_b128 v98, v[48:51] offset:30464
	s_waitcnt lgkmcnt(0)
	s_barrier
	ds_read_b128 v[16:19], v99
	ds_read_b128 v[20:23], v99 offset:4352
	ds_read_b128 v[24:27], v99 offset:8704
	ds_read_b128 v[28:31], v99 offset:13056
	ds_read_b128 v[36:39], v99 offset:17408
	ds_read_b128 v[40:43], v99 offset:21760
	ds_read_b128 v[44:47], v99 offset:26112
	ds_read_b128 v[48:51], v99 offset:30464
	s_waitcnt vmcnt(19) lgkmcnt(7)
	v_mfma_f32_16x16x32_bf16 v[16:19], v[32:35], v[16:19], 0
	s_add_i32 s59, s59, s52
	s_cmpk_gt_i32 s59, 0x7ff
	s_cselect_b64 s[26:27], -1, 0
	s_waitcnt lgkmcnt(6)
	v_mfma_f32_16x16x32_bf16 v[20:23], v[32:35], v[20:23], 0
	s_cmpk_lt_i32 s59, 0x800
	s_cselect_b32 s28, s59, s2
	s_and_b32 s29, s28, 7
	s_waitcnt lgkmcnt(5)
	v_mfma_f32_16x16x32_bf16 v[24:27], v[32:35], v[24:27], 0
	s_lshl_b32 s24, s29, 16
	s_waitcnt lgkmcnt(4)
	v_mfma_f32_16x16x32_bf16 v[28:31], v[32:35], v[28:31], 0
	s_waitcnt lgkmcnt(3)
	v_mfma_f32_16x16x32_bf16 v[36:39], v[32:35], v[36:39], 0
	s_waitcnt lgkmcnt(2)
	v_mfma_f32_16x16x32_bf16 v[40:43], v[32:35], v[40:43], 0
	s_waitcnt lgkmcnt(1)
	v_mfma_f32_16x16x32_bf16 v[44:47], v[32:35], v[44:47], 0
	s_waitcnt lgkmcnt(0)
	v_mfma_f32_16x16x32_bf16 v[32:35], v[32:35], v[48:51], 0
	ds_read_b128 v[48:51], v88 offset:64
	ds_read_b128 v[102:105], v88 offset:128
	s_waitcnt vmcnt(18) lgkmcnt(1)
	v_mfma_f32_16x16x32_bf16 v[16:19], v[12:15], v[48:51], v[16:19]
	ds_read_b128 v[48:51], v89 offset:64
	ds_read_b128 v[106:109], v88 offset:192
	s_waitcnt lgkmcnt(1)
	v_mfma_f32_16x16x32_bf16 v[20:23], v[12:15], v[48:51], v[20:23]
	ds_read_b128 v[48:51], v90 offset:64
	ds_read_b128 v[110:113], v90 offset:128
	s_waitcnt lgkmcnt(1)
	v_mfma_f32_16x16x32_bf16 v[24:27], v[12:15], v[48:51], v[24:27]
	ds_read_b128 v[48:51], v91 offset:64
	ds_read_b128 v[114:117], v90 offset:192
	s_waitcnt vmcnt(17)
	v_mfma_f32_16x16x32_bf16 v[16:19], v[8:11], v[102:105], v[16:19]
	s_waitcnt lgkmcnt(1)
	v_mfma_f32_16x16x32_bf16 v[28:31], v[12:15], v[48:51], v[28:31]
	ds_read_b128 v[48:51], v92 offset:64
	ds_read_b128 v[118:121], v93 offset:64
	ds_read_b128 v[122:125], v92 offset:128
	s_waitcnt vmcnt(16)
	v_mfma_f32_16x16x32_bf16 v[16:19], v[4:7], v[106:109], v[16:19]
	s_waitcnt lgkmcnt(2)
	v_mfma_f32_16x16x32_bf16 v[36:39], v[12:15], v[48:51], v[36:39]
	ds_read_b128 v[48:51], v94 offset:64
	ds_read_b128 v[126:129], v94 offset:128
	ds_read_b128 v[130:133], v92 offset:192
	s_nop 2
	v_not_b32_e32 v61, v16
	v_or_b32_e32 v80, 0x80000000, v16
	s_waitcnt lgkmcnt(4)
	v_mfma_f32_16x16x32_bf16 v[40:43], v[12:15], v[118:121], v[40:43]
	ds_read_b128 v[118:121], v89 offset:128
	ds_read_b128 v[134:137], v89 offset:192
	ds_read_b128 v[138:141], v91 offset:128
	ds_read_b128 v[146:149], v91 offset:192
	ds_read_b128 v[102:105], v93 offset:128
	ds_read_b128 v[150:153], v93 offset:192
	ds_read_b128 v[154:157], v95 offset:64
	ds_read_b128 v[158:161], v94 offset:192
	v_cmp_gt_i32_e32 vcc, 0, v16
	s_waitcnt lgkmcnt(10)
	v_mfma_f32_16x16x32_bf16 v[44:47], v[12:15], v[48:51], v[44:47]
	ds_read_b128 v[106:109], v95 offset:128
	ds_read_b128 v[162:165], v95 offset:192
	v_cndmask_b32_e32 v16, v80, v61, vcc
	v_and_b32_e32 v16, 0xffffff80, v16
	s_waitcnt lgkmcnt(3)
	v_mfma_f32_16x16x32_bf16 v[12:15], v[12:15], v[154:157], v[32:35]
	v_bitop3_b32 v48, v71, s44, v16 bitop3:0x36
	v_not_b32_e32 v16, v17
	v_cmp_gt_i32_e32 vcc, 0, v17
	v_or_b32_e32 v32, 0x80000000, v17
	v_or_b32_e32 v17, 0x80000000, v18
	v_cndmask_b32_e32 v16, v32, v16, vcc
	v_and_b32_e32 v16, 0xffffff80, v16
	v_bitop3_b32 v49, v71, s44, v16 bitop3:0x36
	v_not_b32_e32 v16, v18
	v_cmp_gt_i32_e32 vcc, 0, v18
	v_mfma_f32_16x16x32_bf16 v[20:23], v[8:11], v[118:121], v[20:23]
	v_mov_b32_e32 v61, v53
	v_cndmask_b32_e32 v16, v17, v16, vcc
	v_and_b32_e32 v16, 0xffffff80, v16
	v_bitop3_b32 v50, v71, s44, v16 bitop3:0x36
	v_not_b32_e32 v16, v19
	v_or_b32_e32 v17, 0x80000000, v19
	v_cmp_gt_i32_e32 vcc, 0, v19
	v_mfma_f32_16x16x32_bf16 v[32:35], v[8:11], v[122:125], v[36:39]
	s_nop 0
	v_cndmask_b32_e32 v16, v17, v16, vcc
	v_mfma_f32_16x16x32_bf16 v[36:39], v[8:11], v[102:105], v[40:43]
	s_nop 2
	v_and_b32_e32 v40, 0xffffff80, v16
	v_mfma_f32_16x16x32_bf16 v[16:19], v[4:7], v[134:137], v[20:23]
	v_bitop3_b32 v40, v71, s44, v40 bitop3:0x36
	v_mfma_f32_16x16x32_bf16 v[24:27], v[8:11], v[110:113], v[24:27]
	v_mfma_f32_16x16x32_bf16 v[28:31], v[8:11], v[138:141], v[28:31]
	s_nop 4
	v_not_b32_e32 v41, v16
	v_or_b32_e32 v42, 0x80000000, v16
	v_cmp_gt_i32_e32 vcc, 0, v16
	v_mfma_f32_16x16x32_bf16 v[20:23], v[8:11], v[126:129], v[44:47]
	s_nop 0
	v_cndmask_b32_e32 v16, v42, v41, vcc
	v_and_b32_e32 v16, 0xffffff80, v16
	v_bitop3_b32 v16, v71, s45, v16 bitop3:0x36
	ds_write2_b32 v77, v48, v16 offset1:16
	v_not_b32_e32 v16, v17
	v_or_b32_e32 v41, 0x80000000, v17
	v_cmp_gt_i32_e32 vcc, 0, v17
	v_or_b32_e32 v17, 0x80000000, v18
	s_waitcnt lgkmcnt(2)
	v_mfma_f32_16x16x32_bf16 v[8:11], v[8:11], v[106:109], v[12:15]
	v_cndmask_b32_e32 v16, v41, v16, vcc
	v_and_b32_e32 v16, 0xffffff80, v16
	v_bitop3_b32 v16, v71, s45, v16 bitop3:0x36
	ds_write2_b32 v77, v49, v16 offset0:132 offset1:148
	v_not_b32_e32 v16, v18
	v_cmp_gt_i32_e32 vcc, 0, v18
	v_mfma_f32_16x16x32_bf16 v[12:15], v[4:7], v[114:117], v[24:27]
	s_nop 0
	v_cndmask_b32_e32 v16, v17, v16, vcc
	v_and_b32_e32 v16, 0xffffff80, v16
	v_bitop3_b32 v16, v71, s45, v16 bitop3:0x36
	ds_write2_b32 v78, v50, v16 offset0:8 offset1:24
	v_not_b32_e32 v16, v19
	v_or_b32_e32 v17, 0x80000000, v19
	v_cmp_gt_i32_e32 vcc, 0, v19
	v_mfma_f32_16x16x32_bf16 v[24:27], v[4:7], v[146:149], v[28:31]
	s_nop 0
	v_cndmask_b32_e32 v16, v17, v16, vcc
	v_cmp_gt_i32_e32 vcc, 0, v12
	v_mfma_f32_16x16x32_bf16 v[28:31], v[4:7], v[130:133], v[32:35]
	v_mfma_f32_16x16x32_bf16 v[32:35], v[4:7], v[150:153], v[36:39]
	v_mfma_f32_16x16x32_bf16 v[20:23], v[4:7], v[158:161], v[20:23]
	s_waitcnt lgkmcnt(3)
	v_mfma_f32_16x16x32_bf16 v[4:7], v[4:7], v[162:165], v[8:11]
	s_nop 2
	v_and_b32_e32 v8, 0xffffff80, v16
	v_bitop3_b32 v8, v71, s45, v8 bitop3:0x36
	ds_write2_b32 v78, v40, v8 offset0:140 offset1:156
	v_not_b32_e32 v8, v12
	v_or_b32_e32 v9, 0x80000000, v12
	v_cndmask_b32_e32 v8, v9, v8, vcc
	v_not_b32_e32 v9, v13
	v_or_b32_e32 v10, 0x80000000, v13
	v_cmp_gt_i32_e32 vcc, 0, v13
	v_or_b32_e32 v11, 0x80000000, v14
	v_or_b32_e32 v12, 0x80000000, v15
	v_cndmask_b32_e32 v9, v10, v9, vcc
	v_not_b32_e32 v10, v14
	v_cmp_gt_i32_e32 vcc, 0, v14
	v_or_b32_e32 v13, 0x80000000, v24
	v_and_b32_e32 v8, 0xffffff80, v8
	v_cndmask_b32_e32 v10, v11, v10, vcc
	v_not_b32_e32 v11, v15
	v_cmp_gt_i32_e32 vcc, 0, v15
	v_bitop3_b32 v8, v71, s48, v8 bitop3:0x36
	v_and_b32_e32 v9, 0xffffff80, v9
	v_cndmask_b32_e32 v11, v12, v11, vcc
	v_not_b32_e32 v12, v24
	v_cmp_gt_i32_e32 vcc, 0, v24
	v_bitop3_b32 v9, v71, s48, v9 bitop3:0x36
	v_and_b32_e32 v10, 0xffffff80, v10
	v_cndmask_b32_e32 v12, v13, v12, vcc
	v_and_b32_e32 v12, 0xffffff80, v12
	v_bitop3_b32 v12, v71, s49, v12 bitop3:0x36
	ds_write2_b32 v77, v8, v12 offset0:32 offset1:48
	v_not_b32_e32 v8, v25
	v_or_b32_e32 v12, 0x80000000, v25
	v_cmp_gt_i32_e32 vcc, 0, v25
	v_bitop3_b32 v10, v71, s48, v10 bitop3:0x36
	v_and_b32_e32 v11, 0xffffff80, v11
	v_cndmask_b32_e32 v8, v12, v8, vcc
	v_and_b32_e32 v8, 0xffffff80, v8
	v_bitop3_b32 v8, v71, s49, v8 bitop3:0x36
	ds_write2_b32 v77, v9, v8 offset0:164 offset1:180
	v_not_b32_e32 v8, v26
	v_or_b32_e32 v9, 0x80000000, v26
	v_cmp_gt_i32_e32 vcc, 0, v26
	v_bitop3_b32 v11, v71, s48, v11 bitop3:0x36
	v_or_b32_e32 v12, 0x80000000, v31
	v_cndmask_b32_e32 v8, v9, v8, vcc
	v_and_b32_e32 v8, 0xffffff80, v8
	v_bitop3_b32 v8, v71, s49, v8 bitop3:0x36
	ds_write2_b32 v78, v10, v8 offset0:40 offset1:56
	v_not_b32_e32 v8, v27
	v_or_b32_e32 v9, 0x80000000, v27
	v_cmp_gt_i32_e32 vcc, 0, v27
	v_or_b32_e32 v10, 0x80000000, v29
	v_or_b32_e32 v13, 0x80000000, v32
	v_cndmask_b32_e32 v8, v9, v8, vcc
	v_and_b32_e32 v8, 0xffffff80, v8
	v_bitop3_b32 v8, v71, s49, v8 bitop3:0x36
	ds_write2_b32 v78, v11, v8 offset0:172 offset1:188
	v_not_b32_e32 v8, v28
	v_or_b32_e32 v9, 0x80000000, v28
	v_cmp_gt_i32_e32 vcc, 0, v28
	v_or_b32_e32 v11, 0x80000000, v30
	s_nop 0
	v_cndmask_b32_e32 v8, v9, v8, vcc
	v_not_b32_e32 v9, v29
	v_cmp_gt_i32_e32 vcc, 0, v29
	v_and_b32_e32 v8, 0xffffff80, v8
	v_bitop3_b32 v8, v71, 63, v8 bitop3:0x36
	v_cndmask_b32_e32 v9, v10, v9, vcc
	v_not_b32_e32 v10, v30
	v_cmp_gt_i32_e32 vcc, 0, v30
	v_and_b32_e32 v9, 0xffffff80, v9
	v_bitop3_b32 v9, v71, 63, v9 bitop3:0x36
	v_cndmask_b32_e32 v10, v11, v10, vcc
	v_not_b32_e32 v11, v31
	v_cmp_gt_i32_e32 vcc, 0, v31
	v_and_b32_e32 v10, 0xffffff80, v10
	v_bitop3_b32 v10, v71, 63, v10 bitop3:0x36
	v_cndmask_b32_e32 v11, v12, v11, vcc
	v_not_b32_e32 v12, v32
	v_cmp_gt_i32_e32 vcc, 0, v32
	v_and_b32_e32 v11, 0xffffff80, v11
	v_bitop3_b32 v11, v71, 63, v11 bitop3:0x36
	v_cndmask_b32_e32 v12, v13, v12, vcc
	v_and_b32_e32 v12, 0xffffff80, v12
	v_bitop3_b32 v12, v71, 47, v12 bitop3:0x36
	ds_write2_b32 v77, v8, v12 offset0:64 offset1:80
	v_not_b32_e32 v8, v33
	v_or_b32_e32 v12, 0x80000000, v33
	v_cmp_gt_i32_e32 vcc, 0, v33
	v_or_b32_e32 v13, 0x80000000, v4
	s_nop 0
	v_cndmask_b32_e32 v8, v12, v8, vcc
	v_and_b32_e32 v8, 0xffffff80, v8
	v_bitop3_b32 v8, v71, 47, v8 bitop3:0x36
	ds_write2_b32 v77, v9, v8 offset0:196 offset1:212
	v_not_b32_e32 v8, v34
	v_or_b32_e32 v9, 0x80000000, v34
	v_cmp_gt_i32_e32 vcc, 0, v34
	v_or_b32_e32 v12, 0x80000000, v23
	s_nop 0
	v_cndmask_b32_e32 v8, v9, v8, vcc
	v_and_b32_e32 v8, 0xffffff80, v8
	v_bitop3_b32 v8, v71, 47, v8 bitop3:0x36
	ds_write2_b32 v78, v10, v8 offset0:72 offset1:88
	v_not_b32_e32 v8, v35
	v_or_b32_e32 v9, 0x80000000, v35
	v_cmp_gt_i32_e32 vcc, 0, v35
	v_or_b32_e32 v10, 0x80000000, v21
	s_nop 0
	v_cndmask_b32_e32 v8, v9, v8, vcc
	v_and_b32_e32 v8, 0xffffff80, v8
	v_bitop3_b32 v8, v71, 47, v8 bitop3:0x36
	ds_write2_b32 v78, v11, v8 offset0:204 offset1:220
	v_not_b32_e32 v8, v20
	v_or_b32_e32 v9, 0x80000000, v20
	v_cmp_gt_i32_e32 vcc, 0, v20
	v_or_b32_e32 v11, 0x80000000, v22
	s_nop 0
	v_cndmask_b32_e32 v8, v9, v8, vcc
	v_not_b32_e32 v9, v21
	v_cmp_gt_i32_e32 vcc, 0, v21
	v_and_b32_e32 v8, 0xffffff80, v8
	v_bitop3_b32 v8, v71, 31, v8 bitop3:0x36
	v_cndmask_b32_e32 v9, v10, v9, vcc
	v_not_b32_e32 v10, v22
	v_cmp_gt_i32_e32 vcc, 0, v22
	v_and_b32_e32 v9, 0xffffff80, v9
	v_bitop3_b32 v9, v71, 31, v9 bitop3:0x36
	v_cndmask_b32_e32 v10, v11, v10, vcc
	v_not_b32_e32 v11, v23
	v_cmp_gt_i32_e32 vcc, 0, v23
	v_and_b32_e32 v10, 0xffffff80, v10
	v_bitop3_b32 v10, v71, 31, v10 bitop3:0x36
	v_cndmask_b32_e32 v11, v12, v11, vcc
	v_not_b32_e32 v12, v4
	v_cmp_gt_i32_e32 vcc, 0, v4
	v_and_b32_e32 v11, 0xffffff80, v11
	v_bitop3_b32 v11, v71, 31, v11 bitop3:0x36
	v_cndmask_b32_e32 v4, v13, v12, vcc
	v_and_b32_e32 v4, 0xffffff80, v4
	v_bitop3_b32 v4, v71, 15, v4 bitop3:0x36
	ds_write2_b32 v77, v8, v4 offset0:96 offset1:112
	v_not_b32_e32 v4, v5
	v_or_b32_e32 v8, 0x80000000, v5
	v_cmp_gt_i32_e32 vcc, 0, v5
	v_or_b32_e32 v5, 0x80000000, v6
	s_nop 0
	v_cndmask_b32_e32 v4, v8, v4, vcc
	v_and_b32_e32 v4, 0xffffff80, v4
	v_bitop3_b32 v4, v71, 15, v4 bitop3:0x36
	ds_write2_b32 v77, v9, v4 offset0:228 offset1:244
	v_not_b32_e32 v4, v6
	v_cmp_gt_i32_e32 vcc, 0, v6
	s_nop 1
	v_cndmask_b32_e32 v4, v5, v4, vcc
	v_and_b32_e32 v4, 0xffffff80, v4
	v_bitop3_b32 v4, v71, 15, v4 bitop3:0x36
	ds_write2_b32 v78, v10, v4 offset0:104 offset1:120
	v_not_b32_e32 v4, v7
	v_or_b32_e32 v5, 0x80000000, v7
	v_cmp_gt_i32_e32 vcc, 0, v7
	s_nop 1
	v_cndmask_b32_e32 v4, v5, v4, vcc
	v_and_b32_e32 v4, 0xffffff80, v4
	v_bitop3_b32 v4, v71, 15, v4 bitop3:0x36
	ds_write2_b32 v78, v11, v4 offset0:236 offset1:252
	v_lshl_add_u64 v[4:5], v[54:55], 0, s[24:25]
	v_add_co_u32_e32 v6, vcc, s39, v4
	s_waitcnt lgkmcnt(0)
	s_nop 0
	v_addc_co_u32_e32 v7, vcc, 0, v5, vcc
	s_waitcnt vmcnt(0)
	v_mul_f32_e32 v170, s86, v170
	v_mul_f32_e32 v171, s86, v171
	v_mul_f32_e32 v172, s86, v172
	v_mul_f32_e32 v173, s86, v173
	v_mul_f32_e32 v174, s86, v174
	v_mul_f32_e32 v175, s86, v175
	v_mul_f32_e32 v176, s86, v176
	v_mul_f32_e32 v177, s86, v177
	v_mul_f32_e32 v178, s86, v178
	v_mul_f32_e32 v179, s86, v179
	v_mul_f32_e32 v180, s86, v180
	v_mul_f32_e32 v181, s86, v181
	v_mul_f32_e32 v182, s86, v182
	v_mul_f32_e32 v183, s86, v183
	v_mul_f32_e32 v184, s86, v184
	v_mul_f32_e32 v185, s86, v185
	v_mul_f32_e32 v186, s86, v186
	v_mul_f32_e32 v187, s86, v187
	v_mul_f32_e32 v188, s86, v188
	v_mul_f32_e32 v189, s86, v189
	v_mul_f32_e32 v190, s86, v190
	v_mul_f32_e32 v191, s86, v191
	v_mul_f32_e32 v192, s86, v192
	v_mul_f32_e32 v193, s86, v193
	v_mul_f32_e32 v194, s86, v194
	v_mul_f32_e32 v195, s86, v195
	v_mul_f32_e32 v196, s86, v196
	v_mul_f32_e32 v197, s86, v197
	v_mul_f32_e32 v198, s86, v198
	v_mul_f32_e32 v199, s86, v199
	v_mul_f32_e32 v200, s86, v200
	v_mul_f32_e32 v201, s86, v201
	v_mul_f32_e32 v202, s86, v202
	v_mul_f32_e32 v203, s86, v203
	v_mul_f32_e32 v204, s86, v204
	v_mul_f32_e32 v205, s86, v205
	v_mul_f32_e32 v206, s86, v206
	v_mul_f32_e32 v207, s86, v207
	v_mul_f32_e32 v208, s86, v208
	v_mul_f32_e32 v209, s86, v209
	v_mul_f32_e32 v210, s86, v210
	v_mul_f32_e32 v211, s86, v211
	v_mul_f32_e32 v212, s86, v212
	v_mul_f32_e32 v213, s86, v213
	v_mul_f32_e32 v214, s86, v214
	v_mul_f32_e32 v215, s86, v215
	v_mul_f32_e32 v216, s86, v216
	v_mul_f32_e32 v217, s86, v217
	v_mul_f32_e32 v218, s86, v218
	v_mul_f32_e32 v219, s86, v219
	v_mul_f32_e32 v220, s86, v220
	v_mul_f32_e32 v221, s86, v221
	v_mul_f32_e32 v222, s86, v222
	v_mul_f32_e32 v223, s86, v223
	v_mul_f32_e32 v224, s86, v224
	v_mul_f32_e32 v225, s86, v225
	v_mul_f32_e32 v226, s86, v226
	v_mul_f32_e32 v227, s86, v227
	v_mul_f32_e32 v228, s86, v228
	v_mul_f32_e32 v229, s86, v229
	v_mul_f32_e32 v230, s86, v230
	v_mul_f32_e32 v231, s86, v231
	v_mul_f32_e32 v232, s86, v232
	v_mul_f32_e32 v233, s86, v233
	v_cvt_pk_fp8_f32 v236, v170, v171
	v_cvt_pk_fp8_f32 v237, v174, v175
	v_cvt_pk_fp8_f32 v238, v178, v179
	v_cvt_pk_fp8_f32 v239, v182, v183
	v_cvt_pk_fp8_f32 v240, v186, v187
	v_cvt_pk_fp8_f32 v241, v190, v191
	v_cvt_pk_fp8_f32 v242, v194, v195
	v_cvt_pk_fp8_f32 v243, v198, v199
	v_cvt_pk_fp8_f32 v244, v202, v203
	v_cvt_pk_fp8_f32 v245, v206, v207
	v_cvt_pk_fp8_f32 v246, v210, v211
	v_cvt_pk_fp8_f32 v247, v214, v215
	v_cvt_pk_fp8_f32 v248, v218, v219
	v_cvt_pk_fp8_f32 v249, v222, v223
	v_cvt_pk_fp8_f32 v250, v226, v227
	v_cvt_pk_fp8_f32 v251, v230, v231
	v_cvt_pk_fp8_f32 v236, v172, v173 op_sel:[0,0,1]
	v_cvt_pk_fp8_f32 v237, v176, v177 op_sel:[0,0,1]
	v_cvt_pk_fp8_f32 v238, v180, v181 op_sel:[0,0,1]
	v_cvt_pk_fp8_f32 v239, v184, v185 op_sel:[0,0,1]
	v_cvt_pk_fp8_f32 v240, v188, v189 op_sel:[0,0,1]
	v_cvt_pk_fp8_f32 v241, v192, v193 op_sel:[0,0,1]
	v_cvt_pk_fp8_f32 v242, v196, v197 op_sel:[0,0,1]
	v_cvt_pk_fp8_f32 v243, v200, v201 op_sel:[0,0,1]
	v_cvt_pk_fp8_f32 v244, v204, v205 op_sel:[0,0,1]
	v_cvt_pk_fp8_f32 v245, v208, v209 op_sel:[0,0,1]
	v_cvt_pk_fp8_f32 v246, v212, v213 op_sel:[0,0,1]
	v_cvt_pk_fp8_f32 v247, v216, v217 op_sel:[0,0,1]
	v_cvt_pk_fp8_f32 v248, v220, v221 op_sel:[0,0,1]
	v_cvt_pk_fp8_f32 v249, v224, v225 op_sel:[0,0,1]
	v_cvt_pk_fp8_f32 v250, v228, v229 op_sel:[0,0,1]
	v_cvt_pk_fp8_f32 v251, v232, v233 op_sel:[0,0,1]
	s_nop 0
	global_store_dword v235, v236, s[84:85]
	s_add_u32 s84, s84, 0x800
	s_addc_u32 s85, s85, 0
	global_store_dword v235, v237, s[84:85]
	s_add_u32 s84, s84, 0x800
	s_addc_u32 s85, s85, 0
	global_store_dword v235, v238, s[84:85]
	s_add_u32 s84, s84, 0x800
	s_addc_u32 s85, s85, 0
	global_store_dword v235, v239, s[84:85]
	s_add_u32 s84, s84, 0x800
	s_addc_u32 s85, s85, 0
	global_store_dword v235, v240, s[84:85]
	s_add_u32 s84, s84, 0x800
	s_addc_u32 s85, s85, 0
	global_store_dword v235, v241, s[84:85]
	s_add_u32 s84, s84, 0x800
	s_addc_u32 s85, s85, 0
	global_store_dword v235, v242, s[84:85]
	s_add_u32 s84, s84, 0x800
	s_addc_u32 s85, s85, 0
	global_store_dword v235, v243, s[84:85]
	s_add_u32 s84, s84, 0x800
	s_addc_u32 s85, s85, 0
	global_store_dword v235, v244, s[84:85]
	s_add_u32 s84, s84, 0x800
	s_addc_u32 s85, s85, 0
	global_store_dword v235, v245, s[84:85]
	s_add_u32 s84, s84, 0x800
	s_addc_u32 s85, s85, 0
	global_store_dword v235, v246, s[84:85]
	s_add_u32 s84, s84, 0x800
	s_addc_u32 s85, s85, 0
	global_store_dword v235, v247, s[84:85]
	s_add_u32 s84, s84, 0x800
	s_addc_u32 s85, s85, 0
	global_store_dword v235, v248, s[84:85]
	s_add_u32 s84, s84, 0x800
	s_addc_u32 s85, s85, 0
	global_store_dword v235, v249, s[84:85]
	s_add_u32 s84, s84, 0x800
	s_addc_u32 s85, s85, 0
	global_store_dword v235, v250, s[84:85]
	s_add_u32 s84, s84, 0x800
	s_addc_u32 s85, s85, 0
	global_store_dword v235, v251, s[84:85]
	s_barrier
	global_load_dwordx4 v[44:47], v[6:7], off offset:-4096
	global_load_dwordx4 v[36:39], v[6:7], off
	v_add_co_u32_e32 v6, vcc, s38, v4
	s_lshl_b32 s24, s28, 3
	s_nop 0
	v_addc_co_u32_e32 v7, vcc, 0, v5, vcc
	global_load_dwordx4 v[40:43], v[6:7], off offset:-4096
	global_load_dwordx4 v[28:31], v[6:7], off
	v_add_co_u32_e32 v6, vcc, s37, v4
	s_andn2_b32 s24, s24, 63
	s_nop 0
	v_addc_co_u32_e32 v7, vcc, 0, v5, vcc
	global_load_dwordx4 v[32:35], v[6:7], off offset:-4096
	global_load_dwordx4 v[20:23], v[6:7], off
	v_add_co_u32_e32 v6, vcc, s36, v4
	s_nop 1
	v_addc_co_u32_e32 v7, vcc, 0, v5, vcc
	global_load_dwordx4 v[48:51], v[4:5], off
	global_load_dwordx4 v[24:27], v[6:7], off
	v_add_u32_e32 v4, s24, v84
	v_ashrrev_i32_e32 v5, 31, v4
	v_lshlrev_b64 v[4:5], 12, v[4:5]
	v_lshl_add_u64 v[4:5], s[16:17], 0, v[4:5]
	s_lshl_b32 s24, s29, 9
	v_lshl_add_u64 v[4:5], v[4:5], 0, s[24:25]
	v_lshl_add_u64 v[4:5], v[4:5], 0, v[60:61]
	global_load_dwordx4 v[16:19], v[4:5], off
	global_load_dwordx4 v[12:15], v[4:5], off offset:64
	global_load_dwordx4 v[8:11], v[4:5], off offset:128
	s_nop 0
	global_load_dwordx4 v[4:7], v[4:5], off offset:192
	ds_read_b128 v[102:105], v87 offset:34816
	ds_read_b128 v[106:109], v87 offset:34832
	ds_read_b128 v[110:113], v87 offset:34848
	ds_read_b128 v[114:117], v87 offset:34864
	s_waitcnt lgkmcnt(3)
	v_max_u32_e32 v61, v102, v103
	v_max_u32_e32 v77, v104, v105
	s_waitcnt lgkmcnt(2)
	v_max_u32_e32 v78, v108, v109
	ds_read_b128 v[102:105], v87 offset:34880
	v_max3_u32 v78, v106, v107, v78
	ds_read_b128 v[106:109], v87 offset:34896
	v_max3_u32 v61, v61, v77, v78
	s_waitcnt lgkmcnt(3)
	v_max_u32_e32 v77, v112, v113
	s_waitcnt lgkmcnt(2)
	v_max_u32_e32 v78, v116, v117
	v_max3_u32 v77, v110, v111, v77
	v_max3_u32 v78, v114, v115, v78
	v_max3_u32 v61, v61, v77, v78
	s_waitcnt lgkmcnt(1)
	v_max_u32_e32 v77, v104, v105
	v_max3_u32 v77, v102, v103, v77
	ds_read_b128 v[102:105], v87 offset:34912
	s_waitcnt lgkmcnt(1)
	v_max_u32_e32 v78, v108, v109
	ds_read_b128 v[108:111], v87 offset:34928
	v_max3_u32 v78, v106, v107, v78
	v_max3_u32 v61, v61, v77, v78
	s_waitcnt lgkmcnt(1)
	v_max_u32_e32 v77, v104, v105
	v_max3_u32 v77, v102, v103, v77
	s_waitcnt lgkmcnt(0)
	v_max_u32_e32 v78, v110, v111
	v_max3_u32 v78, v108, v109, v78
	v_max3_u32 v112, v61, v77, v78
	ds_bpermute_b32 v61, v96, v112
	s_waitcnt lgkmcnt(0)
	v_max_u32_e32 v61, v112, v61
	ds_bpermute_b32 v77, v97, v61
	s_waitcnt lgkmcnt(0)
	v_max_u32_e32 v61, v61, v77
	v_not_b32_e32 v77, v61
	v_bfe_u32 v77, v77, 5, 2
	v_cmp_eq_u32_e32 vcc, v77, v83
	s_and_saveexec_b64 s[28:29], vcc
	s_cbranch_execz .LBB0_763
	v_bitop3_b32 v77, v61, s44, v61 bitop3:0xc
	v_lshl_add_u32 v78, v77, 2, v85
	ds_write_b32 v78, v53 offset:34816
	ds_write_b8 v86, v77 offset:16
	ds_read_b128 v[102:105], v87 offset:34816
	ds_read_b128 v[106:109], v87 offset:34832
	ds_read_b128 v[110:113], v87 offset:34848
	ds_read_b128 v[114:117], v87 offset:34864
	ds_read_b128 v[118:121], v87 offset:34880
	ds_read_b128 v[122:125], v87 offset:34896
	ds_read_b128 v[126:129], v87 offset:34912
	ds_read_b128 v[130:133], v87 offset:34928
	s_waitcnt lgkmcnt(6)
	v_max_u32_e32 v80, v108, v109
	v_max_u32_e32 v77, v102, v103
	v_max_u32_e32 v78, v104, v105
	v_max3_u32 v80, v106, v107, v80
	v_max3_u32 v77, v77, v78, v80
	s_waitcnt lgkmcnt(5)
	v_max_u32_e32 v78, v112, v113
	s_waitcnt lgkmcnt(4)
	v_max_u32_e32 v80, v116, v117
	v_max3_u32 v78, v110, v111, v78
	v_max3_u32 v80, v114, v115, v80
	v_max3_u32 v77, v77, v78, v80
	s_waitcnt lgkmcnt(3)
	v_max_u32_e32 v78, v120, v121
	s_waitcnt lgkmcnt(2)
	v_max_u32_e32 v80, v124, v125
	v_max3_u32 v78, v118, v119, v78
	v_max3_u32 v80, v122, v123, v80
	v_max3_u32 v77, v77, v78, v80
	s_waitcnt lgkmcnt(1)
	v_max_u32_e32 v78, v128, v129
	s_waitcnt lgkmcnt(0)
	v_max_u32_e32 v80, v132, v133
	v_max3_u32 v78, v126, v127, v78
	v_max3_u32 v80, v130, v131, v80
	v_max3_u32 v112, v77, v78, v80
